# branch-merge phase: weight rows permuted in the LDS image so gates load as 8 dwordx4 (was 16 dwordx2) and the merged tile stores 16 B per lane without lane swaps
# speedup vs baseline: 1.0113x; 1.0113x over previous
; #define LAS __attribute__((address_space(3)))
; __device__ __forceinline__ int ltid(int wv) { unsigned z = 0u; asm volatile("" : "+v"(z)); return wv * 64 + (int)__builtin_amdgcn_mbcnt_hi(~0u, __builtin_amdgcn_mbcnt_lo(~0u, z)); }
; __device__ __forceinline__ int lgrid() { int g = gridDim.x; asm volatile("" : "+s"(g)); return g; }
; __device__ __forceinline__ int lbid() { int b = blockIdx.x; asm volatile("" : "+s"(b)); return b; }
; __device__ __forceinline__ void branch_phase(LAS unsigned char* lds, const bf16_t* __restrict__ O, const bf16_t* __restrict__ Wb, const bf16_t* __restrict__ Gt, bf16_t* __restrict__ MG, int tg, int wv) {
;     const int tid = ltid(wv), lane = tid & 63, wave = tid >> 6, wm = wave >> 2, wn = wave & 3, fr = lane & 15, fq = lane >> 4;
;     const int G_ = lgrid(), b_ = lbid(), vb = (G_ % 8 == 0) ? (b_ % 8) * (G_ / 8) + b_ / 8 : b_;
;     const int ntile = (tg / 128) * 4;
;     constexpr int STG = 49152;
;     int pR[2], pC[2];
; #pragma unroll
;     for (int i = 0; i < 2; ++i) pg8::stage_rc(tid * 16 + i * 8192, pR[i], pC[i]);
;     const int aoff = pg8::lds_byte(wm * 64 + fr, fq * 8), boff = 16384 + (wn >> 1) * 16384 + pg8::lds_byte((wn & 1) * 64 + fr, fq * 8);
;     __syncthreads();
;     for (int tile = vb; tile < ntile; tile += G_) {
;         const int rt = tile >> 2, ct = tile & 3;
;         const bf16_t* Ab = O + (size_t)(rt * 128) * 1024;
;         u32x2 sum[4][4];
; #pragma unroll
;         for (int m = 0; m < 4; ++m)
; #pragma unroll
;             for (int n = 0; n < 4; ++n) sum[m][n] = (u32x2){0u, 0u};
;     ...
;         BR_LOAD(0, 0);
;         asm volatile("s_waitcnt vmcnt(0)" ::: "memory"); __syncthreads();
.LBB0_276:
	s_lshr_b32 s6, s51, 5
	s_cmp_ge_i32 s5, s6
	s_waitcnt vmcnt(0) lgkmcnt(0)
	s_barrier
	s_cbranch_scc1 .LBB0_283
	v_mbcnt_lo_u32_b32 v196, -1, 0
	v_mbcnt_hi_u32_b32 v196, -1, v196
	v_readlane_b32 s78, v255, 1
	s_nop 1
	s_lshr_b32 s9, s78, 6
	s_lshl_b32 s78, s78, 4
	v_lshlrev_b32_e32 v206, 4, v196
	v_and_b32_e32 v207, 32, v196
	v_xor_b32_e32 v206, v206, v207
	v_lshrrev_b32_e32 v207, 6, v206
	s_lshr_b32 s10, s9, 1
	s_lshl_b32 s10, s10, 4
	v_add_u32_e32 v207, s10, v207
	v_and_b32_e32 v208, 63, v206
	v_lshrrev_b32_e32 v208, 1, v208
	s_and_b32 s10, s9, 1
	s_lshl_b32 s10, s10, 5
	v_add_u32_e32 v208, s10, v208
	v_lshlrev_b32_e32 v208, 1, v208
	v_lshl_add_u32 v197, v207, 11, v208
	v_add_u32_e32 v198, 0x20000, v197
	v_and_b32_e32 v209, 3, v207
	v_lshrrev_b32_e32 v210, 2, v207
	v_and_b32_e32 v210, 3, v210
	v_lshl_or_b32 v209, v210, 3, v209
	v_lshrrev_b32_e32 v210, 4, v207
	v_and_b32_e32 v210, 1, v210
	v_lshl_or_b32 v209, v210, 2, v209
	v_and_b32_e32 v210, 32, v207
	v_or_b32_e32 v209, v209, v210
	v_lshl_add_u32 v199, v209, 9, v208
	v_add_u32_e32 v200, 0x8000, v199
	v_and_b32_e32 v206, 15, v196
	v_lshrrev_b32_e32 v207, 4, v196
	v_lshlrev_b32_e32 v208, 6, v206
	v_lshl_add_u32 v208, v207, 4, v208
	v_lshlrev_b32_e32 v209, 2, v206
	v_and_b32_e32 v209, 32, v209
	v_xor_b32_e32 v208, v208, v209
	s_lshr_b32 s10, s9, 2
	s_lshl_b32 s11, s10, 13
	v_add_u32_e32 v201, s11, v208
	s_and_b32 s11, s9, 3
	s_and_b32 s12, s11, 1
	s_lshl_b32 s12, s12, 13
	s_lshr_b32 s13, s11, 1
	s_lshl_b32 s21, s13, 14
	s_add_i32 s12, s12, s21
	s_add_i32 s12, s12, 0x4000
	v_add_u32_e32 v202, s12, v208
	s_lshl_b32 s21, s13, 11
	v_add_u32_e32 v203, s21, v202
	v_add_u32_e32 v214, 0x0, v201
	v_add_u32_e32 v217, 0x0, v202
	v_add_u32_e32 v215, 0xc000, v201
	v_add_u32_e32 v218, 0xc000, v202
	v_add_u32_e32 v216, 0x18000, v201
	v_add_u32_e32 v219, 0x18000, v203
	s_add_i32 s82, s78, 0x0
	s_add_i32 s85, s78, 0x8000
	s_add_i32 s83, s78, 0xc000
	s_add_i32 s60, s78, 0x14000
	s_add_i32 s84, s78, 0x18000
	s_add_i32 s61, s78, 0x20800
	s_lshl_b32 s12, s10, 6
	v_add_u32_e32 v210, s12, v206
	s_lshl_b32 s12, s11, 7
	v_lshl_add_u32 v211, v207, 4, s12
	v_lshl_add_u32 v204, v210, 13, v211
	v_lshl_add_u32 v205, v210, 11, v211
	s_lshr_b32 s9, s5, 2
	s_and_b32 s10, s5, 3
	s_lshl_b32 s11, s9, 18
	s_add_u32 s64, s18, s11
	s_addc_u32 s65, s19, 0
	s_add_u32 s64, s64, 0x1e200000
	s_addc_u32 s65, s65, 0
	s_lshl_b32 s11, s10, 17
	s_add_u32 s68, s57, s11
	s_addc_u32 s69, s58, 0
	s_add_u32 s68, s68, 0x1100000
	s_addc_u32 s69, s69, 0
	s_lshl_b32 s11, s9, 20
	s_lshl_b32 s12, s10, 9
	s_add_u32 s74, s18, s11
	s_addc_u32 s75, s19, 0
	s_add_u32 s74, s74, s12
	s_addc_u32 s75, s75, 0
	s_add_u32 s74, s74, 0xa200000
	s_addc_u32 s75, s75, 0
	s_lshl_b32 s11, s9, 18
	s_add_u32 s76, s18, s11
	s_addc_u32 s77, s19, 0
	s_add_u32 s76, s76, s12
	s_addc_u32 s77, s77, 0
	s_add_u32 s76, s76, 0x29400000
	s_addc_u32 s77, s77, 0
	s_lshr_b32 s62, s4, 2
	s_lshl_b32 s62, s62, 18
	s_waitcnt lgkmcnt(0)
	s_barrier
	s_add_u32 s66, s64, 0x0
	s_addc_u32 s67, s65, 0
	s_add_u32 s70, s68, 0x0
	s_addc_u32 s71, s69, 0
	s_add_u32 s72, s70, 0x10000
	s_addc_u32 s73, s71, 0
	s_mov_b32 m0, s82
	s_nop 0
	global_load_lds_dwordx4 v197, s[66:67]
	s_add_i32 m0, s82, 0x2000
	s_nop 0
	global_load_lds_dwordx4 v198, s[66:67]
	s_add_i32 m0, s82, 0x4000
	s_nop 0
	global_load_lds_dwordx4 v199, s[70:71]
	s_add_i32 m0, s82, 0x6000
	s_nop 0
	global_load_lds_dwordx4 v200, s[70:71]
	s_mov_b32 m0, s85
	s_nop 0
	global_load_lds_dwordx4 v199, s[72:73]
	s_add_i32 m0, s85, 0x2000
	s_nop 0
	global_load_lds_dwordx4 v200, s[72:73]
	s_add_u32 s66, s64, 0x80
	s_addc_u32 s67, s65, 0
	s_add_u32 s70, s68, 0x80
	s_addc_u32 s71, s69, 0
	s_add_u32 s72, s70, 0x10000
	s_addc_u32 s73, s71, 0
	s_mov_b32 m0, s83
	s_nop 0
	global_load_lds_dwordx4 v197, s[66:67]
	s_add_i32 m0, s83, 0x2000
	s_nop 0
	global_load_lds_dwordx4 v198, s[66:67]
	s_add_i32 m0, s83, 0x4000
	s_nop 0
	global_load_lds_dwordx4 v199, s[70:71]
	s_add_i32 m0, s83, 0x6000
	s_nop 0
	global_load_lds_dwordx4 v200, s[70:71]
	s_mov_b32 m0, s60
	s_nop 0
	global_load_lds_dwordx4 v199, s[72:73]
	s_add_i32 m0, s60, 0x2000
	s_nop 0
	global_load_lds_dwordx4 v200, s[72:73]
.Lph6_tile:
	v_mov_b64 v[66:67], 0
	v_mov_b64 v[68:69], 0
	v_mov_b64 v[70:71], 0
	v_mov_b64 v[72:73], 0
	v_mov_b64 v[74:75], 0
	v_mov_b64 v[76:77], 0
	v_mov_b64 v[78:79], 0
	v_mov_b64 v[80:81], 0
	v_mov_b64 v[82:83], 0
	v_mov_b64 v[84:85], 0
	v_mov_b64 v[86:87], 0
	v_mov_b64 v[88:89], 0
	v_mov_b64 v[90:91], 0
	v_mov_b64 v[92:93], 0
	v_mov_b64 v[94:95], 0
	v_mov_b64 v[96:97], 0
	s_waitcnt vmcnt(6)
	s_barrier
; #define LAS __attribute__((address_space(3)))
; __device__ __forceinline__ void branch_phase(LAS unsigned char* lds, const bf16_t* __restrict__ O, const bf16_t* __restrict__ Wb, const bf16_t* __restrict__ Gt, bf16_t* __restrict__ MG, int tg, int wv) {
;     ...
;             for (int kc = 0; kc < 4; ++kc) {
;                 const int c = j * 4 + kc;
;                 if (c + 1 < 16) BR_LOAD(c + 1, (c + 1) & 1);
;                 if (kc == 3) {
;                     const bf16_t* gp = Gt + (size_t)(rt * 128 + wm * 64 + fr) * ZC + j * 1024 + ct * 256 + wn * 64 + 4 * fq;
; #pragma unroll
;                     for (int m = 0; m < 4; ++m)
; #pragma unroll
;                         for (int n = 0; n < 4; ++n) gv[m][n] = *(const u32x2*)(gp + (size_t)m * 16 * ZC + n * 16);
;                 }
;                 LAS const unsigned char* st = lds + (c & 1) * STG;
; #pragma unroll
;                 for (int k = 0; k < 2; ++k) {
;                     __builtin_amdgcn_sched_barrier(0);
;                     bf16x8 af[4], bfr[4];
; #pragma unroll
;                     for (int m = 0; m < 4; ++m) af[m] = *(LAS const bf16x8*)(st + aoff + m * 2048 + k * 1024);
; #pragma unroll
;                     for (int n = 0; n < 4; ++n) bfr[n] = *(LAS const bf16x8*)(st + boff + n * 2048 + k * 1024);
; #pragma unroll
;                     for (int m = 0; m < 4; ++m)
; #pragma unroll
;                         for (int n = 0; n < 4; ++n) acc[m][n] = __builtin_amdgcn_mfma_f32_16x16x32_bf16(bfr[n], af[m], acc[m][n], 0, 0, 0);
	s_add_u32 s66, s64, 0x100
	s_addc_u32 s67, s65, 0
	s_add_u32 s70, s68, 0x100
	s_addc_u32 s71, s69, 0
	s_add_u32 s72, s70, 0x10000
	s_addc_u32 s73, s71, 0
	s_mov_b32 m0, s84
	s_nop 0
	global_load_lds_dwordx4 v197, s[66:67]
	s_add_i32 m0, s84, 0x2000
	s_nop 0
	global_load_lds_dwordx4 v198, s[66:67]
	s_add_i32 m0, s84, 0x4000
	s_nop 0
	global_load_lds_dwordx4 v199, s[70:71]
	s_add_i32 m0, s84, 0x6000
	s_nop 0
	global_load_lds_dwordx4 v200, s[70:71]
	s_mov_b32 m0, s61
	s_nop 0
	global_load_lds_dwordx4 v199, s[72:73]
	s_add_i32 m0, s61, 0x2000
	s_nop 0
	global_load_lds_dwordx4 v200, s[72:73]
	ds_read_b128 v[130:133], v214 offset:0
	ds_read_b128 v[134:137], v214 offset:2048
	ds_read_b128 v[138:141], v214 offset:4096
	ds_read_b128 v[142:145], v214 offset:6144
	ds_read_b128 v[162:165], v217 offset:0
	ds_read_b128 v[166:169], v217 offset:2048
	ds_read_b128 v[170:173], v217 offset:4096
	ds_read_b128 v[174:177], v217 offset:6144
	ds_read_b128 v[146:149], v214 offset:1024
	ds_read_b128 v[150:153], v214 offset:3072
	ds_read_b128 v[154:157], v214 offset:5120
	ds_read_b128 v[158:161], v214 offset:7168
	ds_read_b128 v[178:181], v217 offset:1024
	ds_read_b128 v[182:185], v217 offset:3072
	ds_read_b128 v[186:189], v217 offset:5120
	ds_read_b128 v[190:193], v217 offset:7168
	s_waitcnt lgkmcnt(8)
	v_mfma_f32_16x16x32_bf16 v[2:5], v[162:165], v[130:133], 0
	v_mfma_f32_16x16x32_bf16 v[6:9], v[166:169], v[130:133], 0
	v_mfma_f32_16x16x32_bf16 v[10:13], v[170:173], v[130:133], 0
	v_mfma_f32_16x16x32_bf16 v[14:17], v[174:177], v[130:133], 0
	v_mfma_f32_16x16x32_bf16 v[18:21], v[162:165], v[134:137], 0
	v_mfma_f32_16x16x32_bf16 v[22:25], v[166:169], v[134:137], 0
	v_mfma_f32_16x16x32_bf16 v[26:29], v[170:173], v[134:137], 0
	v_mfma_f32_16x16x32_bf16 v[30:33], v[174:177], v[134:137], 0
	v_mfma_f32_16x16x32_bf16 v[34:37], v[162:165], v[138:141], 0
	v_mfma_f32_16x16x32_bf16 v[38:41], v[166:169], v[138:141], 0
	v_mfma_f32_16x16x32_bf16 v[42:45], v[170:173], v[138:141], 0
	v_mfma_f32_16x16x32_bf16 v[46:49], v[174:177], v[138:141], 0
	v_mfma_f32_16x16x32_bf16 v[50:53], v[162:165], v[142:145], 0
	v_mfma_f32_16x16x32_bf16 v[54:57], v[166:169], v[142:145], 0
	v_mfma_f32_16x16x32_bf16 v[58:61], v[170:173], v[142:145], 0
	v_mfma_f32_16x16x32_bf16 v[62:65], v[174:177], v[142:145], 0
	s_waitcnt lgkmcnt(0)
	v_mfma_f32_16x16x32_bf16 v[2:5], v[178:181], v[146:149], v[2:5]
	v_mfma_f32_16x16x32_bf16 v[6:9], v[182:185], v[146:149], v[6:9]
	v_mfma_f32_16x16x32_bf16 v[10:13], v[186:189], v[146:149], v[10:13]
	v_mfma_f32_16x16x32_bf16 v[14:17], v[190:193], v[146:149], v[14:17]
	v_mfma_f32_16x16x32_bf16 v[18:21], v[178:181], v[150:153], v[18:21]
	v_mfma_f32_16x16x32_bf16 v[22:25], v[182:185], v[150:153], v[22:25]
	v_mfma_f32_16x16x32_bf16 v[26:29], v[186:189], v[150:153], v[26:29]
	v_mfma_f32_16x16x32_bf16 v[30:33], v[190:193], v[150:153], v[30:33]
	v_mfma_f32_16x16x32_bf16 v[34:37], v[178:181], v[154:157], v[34:37]
	v_mfma_f32_16x16x32_bf16 v[38:41], v[182:185], v[154:157], v[38:41]
	v_mfma_f32_16x16x32_bf16 v[42:45], v[186:189], v[154:157], v[42:45]
	v_mfma_f32_16x16x32_bf16 v[46:49], v[190:193], v[154:157], v[46:49]
	v_mfma_f32_16x16x32_bf16 v[50:53], v[178:181], v[158:161], v[50:53]
	v_mfma_f32_16x16x32_bf16 v[54:57], v[182:185], v[158:161], v[54:57]
	v_mfma_f32_16x16x32_bf16 v[58:61], v[186:189], v[158:161], v[58:61]
	v_mfma_f32_16x16x32_bf16 v[62:65], v[190:193], v[158:161], v[62:65]
	s_waitcnt vmcnt(6)
	s_barrier
	s_add_u32 s66, s64, 0x180
	s_addc_u32 s67, s65, 0
	s_add_u32 s70, s68, 0x180
	s_addc_u32 s71, s69, 0
	s_add_u32 s72, s70, 0x10000
	s_addc_u32 s73, s71, 0
	s_mov_b32 m0, s82
	s_nop 0
	global_load_lds_dwordx4 v197, s[66:67]
	s_add_i32 m0, s82, 0x2000
	s_nop 0
	global_load_lds_dwordx4 v198, s[66:67]
	s_add_i32 m0, s82, 0x4000
	s_nop 0
	global_load_lds_dwordx4 v199, s[70:71]
	s_add_i32 m0, s82, 0x6000
	s_nop 0
	global_load_lds_dwordx4 v200, s[70:71]
	s_mov_b32 m0, s85
	s_nop 0
	global_load_lds_dwordx4 v199, s[72:73]
	s_add_i32 m0, s85, 0x2000
	s_nop 0
	global_load_lds_dwordx4 v200, s[72:73]
	s_add_u32 s80, s74, 0x0
	s_addc_u32 s81, s75, 0
	global_load_dwordx4 v[98:101], v204, s[80:81] offset:0
	global_load_dwordx4 v[102:105], v204, s[80:81] offset:64
	s_add_u32 s80, s80, 0x20000
	s_addc_u32 s81, s81, 0
	global_load_dwordx4 v[106:109], v204, s[80:81] offset:0
	global_load_dwordx4 v[110:113], v204, s[80:81] offset:64
	s_add_u32 s80, s80, 0x20000
	s_addc_u32 s81, s81, 0
	global_load_dwordx4 v[114:117], v204, s[80:81] offset:0
	global_load_dwordx4 v[118:121], v204, s[80:81] offset:64
	s_add_u32 s80, s80, 0x20000
	s_addc_u32 s81, s81, 0
	global_load_dwordx4 v[122:125], v204, s[80:81] offset:0
	global_load_dwordx4 v[126:129], v204, s[80:81] offset:64
	ds_read_b128 v[130:133], v215 offset:0
	ds_read_b128 v[134:137], v215 offset:2048
	ds_read_b128 v[138:141], v215 offset:4096
	ds_read_b128 v[142:145], v215 offset:6144
	ds_read_b128 v[162:165], v218 offset:0
	ds_read_b128 v[166:169], v218 offset:2048
	ds_read_b128 v[170:173], v218 offset:4096
	ds_read_b128 v[174:177], v218 offset:6144
	ds_read_b128 v[146:149], v215 offset:1024
	ds_read_b128 v[150:153], v215 offset:3072
	ds_read_b128 v[154:157], v215 offset:5120
	ds_read_b128 v[158:161], v215 offset:7168
	ds_read_b128 v[178:181], v218 offset:1024
	ds_read_b128 v[182:185], v218 offset:3072
	ds_read_b128 v[186:189], v218 offset:5120
	ds_read_b128 v[190:193], v218 offset:7168
	s_waitcnt lgkmcnt(8)
; #define LAS __attribute__((address_space(3)))
; __device__ __forceinline__ void branch_phase(LAS unsigned char* lds, const bf16_t* __restrict__ O, const bf16_t* __restrict__ Wb, const bf16_t* __restrict__ Gt, bf16_t* __restrict__ MG, int tg, int wv) {
;     ...
;                 LAS const unsigned char* st = lds + (c & 1) * STG;
; #pragma unroll
;                 for (int k = 0; k < 2; ++k) {
;                     __builtin_amdgcn_sched_barrier(0);
;                     bf16x8 af[4], bfr[4];
; #pragma unroll
;                     for (int m = 0; m < 4; ++m) af[m] = *(LAS const bf16x8*)(st + aoff + m * 2048 + k * 1024);
; #pragma unroll
;                     for (int n = 0; n < 4; ++n) bfr[n] = *(LAS const bf16x8*)(st + boff + n * 2048 + k * 1024);
; #pragma unroll
;                     for (int m = 0; m < 4; ++m)
; #pragma unroll
;                         for (int n = 0; n < 4; ++n) acc[m][n] = __builtin_amdgcn_mfma_f32_16x16x32_bf16(bfr[n], af[m], acc[m][n], 0, 0, 0);
;                 }
;                 asm volatile("s_waitcnt vmcnt(0)" ::: "memory"); __syncthreads();
;             }
	v_mfma_f32_16x16x32_bf16 v[2:5], v[162:165], v[130:133], v[2:5]
	v_mfma_f32_16x16x32_bf16 v[6:9], v[166:169], v[130:133], v[6:9]
	v_mfma_f32_16x16x32_bf16 v[10:13], v[170:173], v[130:133], v[10:13]
	v_mfma_f32_16x16x32_bf16 v[14:17], v[174:177], v[130:133], v[14:17]
	v_mfma_f32_16x16x32_bf16 v[18:21], v[162:165], v[134:137], v[18:21]
	v_mfma_f32_16x16x32_bf16 v[22:25], v[166:169], v[134:137], v[22:25]
	v_mfma_f32_16x16x32_bf16 v[26:29], v[170:173], v[134:137], v[26:29]
	v_mfma_f32_16x16x32_bf16 v[30:33], v[174:177], v[134:137], v[30:33]
	v_mfma_f32_16x16x32_bf16 v[34:37], v[162:165], v[138:141], v[34:37]
	v_mfma_f32_16x16x32_bf16 v[38:41], v[166:169], v[138:141], v[38:41]
	v_mfma_f32_16x16x32_bf16 v[42:45], v[170:173], v[138:141], v[42:45]
	v_mfma_f32_16x16x32_bf16 v[46:49], v[174:177], v[138:141], v[46:49]
	v_mfma_f32_16x16x32_bf16 v[50:53], v[162:165], v[142:145], v[50:53]
	v_mfma_f32_16x16x32_bf16 v[54:57], v[166:169], v[142:145], v[54:57]
	v_mfma_f32_16x16x32_bf16 v[58:61], v[170:173], v[142:145], v[58:61]
	v_mfma_f32_16x16x32_bf16 v[62:65], v[174:177], v[142:145], v[62:65]
	s_waitcnt lgkmcnt(0)
	v_mfma_f32_16x16x32_bf16 v[2:5], v[178:181], v[146:149], v[2:5]
	v_mfma_f32_16x16x32_bf16 v[6:9], v[182:185], v[146:149], v[6:9]
	v_mfma_f32_16x16x32_bf16 v[10:13], v[186:189], v[146:149], v[10:13]
	v_mfma_f32_16x16x32_bf16 v[14:17], v[190:193], v[146:149], v[14:17]
	v_mfma_f32_16x16x32_bf16 v[18:21], v[178:181], v[150:153], v[18:21]
	v_mfma_f32_16x16x32_bf16 v[22:25], v[182:185], v[150:153], v[22:25]
	v_mfma_f32_16x16x32_bf16 v[26:29], v[186:189], v[150:153], v[26:29]
	v_mfma_f32_16x16x32_bf16 v[30:33], v[190:193], v[150:153], v[30:33]
	v_mfma_f32_16x16x32_bf16 v[34:37], v[178:181], v[154:157], v[34:37]
	v_mfma_f32_16x16x32_bf16 v[38:41], v[182:185], v[154:157], v[38:41]
	v_mfma_f32_16x16x32_bf16 v[42:45], v[186:189], v[154:157], v[42:45]
	v_mfma_f32_16x16x32_bf16 v[46:49], v[190:193], v[154:157], v[46:49]
	v_mfma_f32_16x16x32_bf16 v[50:53], v[178:181], v[158:161], v[50:53]
	v_mfma_f32_16x16x32_bf16 v[54:57], v[182:185], v[158:161], v[54:57]
	v_mfma_f32_16x16x32_bf16 v[58:61], v[186:189], v[158:161], v[58:61]
	v_mfma_f32_16x16x32_bf16 v[62:65], v[190:193], v[158:161], v[62:65]
	s_waitcnt vmcnt(14)
	s_barrier
	s_add_u32 s66, s64, 0x200
	s_addc_u32 s67, s65, 0
	s_add_u32 s70, s68, 0x80000
	s_addc_u32 s71, s69, 0
	s_add_u32 s72, s70, 0x10000
	s_addc_u32 s73, s71, 0
	s_mov_b32 m0, s83
	s_nop 0
	global_load_lds_dwordx4 v197, s[66:67]
	s_add_i32 m0, s83, 0x2000
	s_nop 0
	global_load_lds_dwordx4 v198, s[66:67]
	s_add_i32 m0, s83, 0x4000
	s_nop 0
	global_load_lds_dwordx4 v199, s[70:71]
	s_add_i32 m0, s83, 0x6000
	s_nop 0
	global_load_lds_dwordx4 v200, s[70:71]
	s_mov_b32 m0, s60
	s_nop 0
	global_load_lds_dwordx4 v199, s[72:73]
	s_add_i32 m0, s60, 0x2000
	s_nop 0
	global_load_lds_dwordx4 v200, s[72:73]
	ds_read_b128 v[130:133], v216 offset:0
	ds_read_b128 v[134:137], v216 offset:2048
	ds_read_b128 v[138:141], v216 offset:4096
	ds_read_b128 v[142:145], v216 offset:6144
	ds_read_b128 v[162:165], v219 offset:0
	ds_read_b128 v[166:169], v219 offset:2048
	ds_read_b128 v[170:173], v219 offset:4096
	ds_read_b128 v[174:177], v219 offset:6144
	ds_read_b128 v[146:149], v216 offset:1024
	ds_read_b128 v[150:153], v216 offset:3072
	ds_read_b128 v[154:157], v216 offset:5120
	ds_read_b128 v[158:161], v216 offset:7168
	ds_read_b128 v[178:181], v219 offset:1024
	ds_read_b128 v[182:185], v219 offset:3072
	ds_read_b128 v[186:189], v219 offset:5120
	ds_read_b128 v[190:193], v219 offset:7168
	s_waitcnt lgkmcnt(8)
	v_mfma_f32_16x16x32_bf16 v[2:5], v[162:165], v[130:133], v[2:5]
	v_mfma_f32_16x16x32_bf16 v[6:9], v[166:169], v[130:133], v[6:9]
	v_mfma_f32_16x16x32_bf16 v[10:13], v[170:173], v[130:133], v[10:13]
	v_mfma_f32_16x16x32_bf16 v[14:17], v[174:177], v[130:133], v[14:17]
	v_mfma_f32_16x16x32_bf16 v[18:21], v[162:165], v[134:137], v[18:21]
	v_mfma_f32_16x16x32_bf16 v[22:25], v[166:169], v[134:137], v[22:25]
	v_mfma_f32_16x16x32_bf16 v[26:29], v[170:173], v[134:137], v[26:29]
	v_mfma_f32_16x16x32_bf16 v[30:33], v[174:177], v[134:137], v[30:33]
	v_mfma_f32_16x16x32_bf16 v[34:37], v[162:165], v[138:141], v[34:37]
	v_mfma_f32_16x16x32_bf16 v[38:41], v[166:169], v[138:141], v[38:41]
	v_mfma_f32_16x16x32_bf16 v[42:45], v[170:173], v[138:141], v[42:45]
	v_mfma_f32_16x16x32_bf16 v[46:49], v[174:177], v[138:141], v[46:49]
	v_mfma_f32_16x16x32_bf16 v[50:53], v[162:165], v[142:145], v[50:53]
	v_mfma_f32_16x16x32_bf16 v[54:57], v[166:169], v[142:145], v[54:57]
	v_mfma_f32_16x16x32_bf16 v[58:61], v[170:173], v[142:145], v[58:61]
	v_mfma_f32_16x16x32_bf16 v[62:65], v[174:177], v[142:145], v[62:65]
	s_waitcnt lgkmcnt(0)
	v_mfma_f32_16x16x32_bf16 v[2:5], v[178:181], v[146:149], v[2:5]
	v_mfma_f32_16x16x32_bf16 v[6:9], v[182:185], v[146:149], v[6:9]
	v_mfma_f32_16x16x32_bf16 v[10:13], v[186:189], v[146:149], v[10:13]
	v_mfma_f32_16x16x32_bf16 v[14:17], v[190:193], v[146:149], v[14:17]
	v_mfma_f32_16x16x32_bf16 v[18:21], v[178:181], v[150:153], v[18:21]
	v_mfma_f32_16x16x32_bf16 v[22:25], v[182:185], v[150:153], v[22:25]
	v_mfma_f32_16x16x32_bf16 v[26:29], v[186:189], v[150:153], v[26:29]
	v_mfma_f32_16x16x32_bf16 v[30:33], v[190:193], v[150:153], v[30:33]
	v_mfma_f32_16x16x32_bf16 v[34:37], v[178:181], v[154:157], v[34:37]
	v_mfma_f32_16x16x32_bf16 v[38:41], v[182:185], v[154:157], v[38:41]
	v_mfma_f32_16x16x32_bf16 v[42:45], v[186:189], v[154:157], v[42:45]
	v_mfma_f32_16x16x32_bf16 v[46:49], v[190:193], v[154:157], v[46:49]
	v_mfma_f32_16x16x32_bf16 v[50:53], v[178:181], v[158:161], v[50:53]
	v_mfma_f32_16x16x32_bf16 v[54:57], v[182:185], v[158:161], v[54:57]
	v_mfma_f32_16x16x32_bf16 v[58:61], v[186:189], v[158:161], v[58:61]
	v_mfma_f32_16x16x32_bf16 v[62:65], v[190:193], v[158:161], v[62:65]
	s_waitcnt vmcnt(14)
	s_barrier
; #define LAS __attribute__((address_space(3)))
; __device__ __forceinline__ unsigned cvtpk(float lo, float hi) { f32x2 v = {lo, hi}; bf16x2_t b = __builtin_convertvector(v, bf16x2_t); return __builtin_bit_cast(unsigned, b); }
; __device__ __forceinline__ void branch_phase(LAS unsigned char* lds, const bf16_t* __restrict__ O, const bf16_t* __restrict__ Wb, const bf16_t* __restrict__ Gt, bf16_t* __restrict__ MG, int tg, int wv) {
;     ...
;                 LAS const unsigned char* st = lds + (c & 1) * STG;
; #pragma unroll
;                 for (int k = 0; k < 2; ++k) {
;                     __builtin_amdgcn_sched_barrier(0);
;                     bf16x8 af[4], bfr[4];
; #pragma unroll
;                     for (int m = 0; m < 4; ++m) af[m] = *(LAS const bf16x8*)(st + aoff + m * 2048 + k * 1024);
; #pragma unroll
;                     for (int n = 0; n < 4; ++n) bfr[n] = *(LAS const bf16x8*)(st + boff + n * 2048 + k * 1024);
; #pragma unroll
;                     for (int m = 0; m < 4; ++m)
; #pragma unroll
;                         for (int n = 0; n < 4; ++n) acc[m][n] = __builtin_amdgcn_mfma_f32_16x16x32_bf16(bfr[n], af[m], acc[m][n], 0, 0, 0);
;                 }
;                 asm volatile("s_waitcnt vmcnt(0)" ::: "memory"); __syncthreads();
;             }
; #pragma unroll
;             for (int m = 0; m < 4; ++m)
; #pragma unroll
;                 for (int n = 0; n < 4; ++n) { const u32x2 g = gv[m][n], sp = sum[m][n];
;                     const float s0_ = __builtin_bit_cast(float, sp.x << 16) + acc[m][n][0] * __builtin_bit_cast(float, g.x << 16), s1_ = __builtin_bit_cast(float, sp.x & 0xffff0000u) + acc[m][n][1] * __builtin_bit_cast(float, g.x & 0xffff0000u);
;                     const float s2_ = __builtin_bit_cast(float, sp.y << 16) + acc[m][n][2] * __builtin_bit_cast(float, g.y << 16), s3_ = __builtin_bit_cast(float, sp.y & 0xffff0000u) + acc[m][n][3] * __builtin_bit_cast(float, g.y & 0xffff0000u);
;                     sum[m][n] = (u32x2){cvtpk(s0_, s1_), cvtpk(s2_, s3_)}; }
	s_add_u32 s66, s64, 0x280
	s_addc_u32 s67, s65, 0
	s_add_u32 s70, s68, 0x80080
	s_addc_u32 s71, s69, 0
	s_add_u32 s72, s70, 0x10000
	s_addc_u32 s73, s71, 0
	s_mov_b32 m0, s84
	s_nop 0
	global_load_lds_dwordx4 v197, s[66:67]
	s_add_i32 m0, s84, 0x2000
	s_nop 0
	global_load_lds_dwordx4 v198, s[66:67]
	s_add_i32 m0, s84, 0x4000
	s_nop 0
	global_load_lds_dwordx4 v199, s[70:71]
	s_add_i32 m0, s84, 0x6000
	s_nop 0
	global_load_lds_dwordx4 v200, s[70:71]
	s_mov_b32 m0, s61
	s_nop 0
	global_load_lds_dwordx4 v199, s[72:73]
	s_add_i32 m0, s61, 0x2000
	s_nop 0
	global_load_lds_dwordx4 v200, s[72:73]
	ds_read_b128 v[130:133], v214 offset:0
	ds_read_b128 v[134:137], v214 offset:2048
	ds_read_b128 v[138:141], v214 offset:4096
	ds_read_b128 v[142:145], v214 offset:6144
	ds_read_b128 v[162:165], v217 offset:0
	ds_read_b128 v[166:169], v217 offset:2048
	ds_read_b128 v[170:173], v217 offset:4096
	ds_read_b128 v[174:177], v217 offset:6144
	ds_read_b128 v[146:149], v214 offset:1024
	ds_read_b128 v[150:153], v214 offset:3072
	ds_read_b128 v[154:157], v214 offset:5120
	ds_read_b128 v[158:161], v214 offset:7168
	ds_read_b128 v[178:181], v217 offset:1024
	ds_read_b128 v[182:185], v217 offset:3072
	ds_read_b128 v[186:189], v217 offset:5120
	ds_read_b128 v[190:193], v217 offset:7168
	s_waitcnt lgkmcnt(8)
	v_mfma_f32_16x16x32_bf16 v[2:5], v[162:165], v[130:133], v[2:5]
	v_mfma_f32_16x16x32_bf16 v[6:9], v[166:169], v[130:133], v[6:9]
	v_mfma_f32_16x16x32_bf16 v[10:13], v[170:173], v[130:133], v[10:13]
	v_mfma_f32_16x16x32_bf16 v[14:17], v[174:177], v[130:133], v[14:17]
	v_mfma_f32_16x16x32_bf16 v[18:21], v[162:165], v[134:137], v[18:21]
	v_mfma_f32_16x16x32_bf16 v[22:25], v[166:169], v[134:137], v[22:25]
	v_mfma_f32_16x16x32_bf16 v[26:29], v[170:173], v[134:137], v[26:29]
	v_mfma_f32_16x16x32_bf16 v[30:33], v[174:177], v[134:137], v[30:33]
	v_mfma_f32_16x16x32_bf16 v[34:37], v[162:165], v[138:141], v[34:37]
	v_mfma_f32_16x16x32_bf16 v[38:41], v[166:169], v[138:141], v[38:41]
	v_mfma_f32_16x16x32_bf16 v[42:45], v[170:173], v[138:141], v[42:45]
	v_mfma_f32_16x16x32_bf16 v[46:49], v[174:177], v[138:141], v[46:49]
	v_mfma_f32_16x16x32_bf16 v[50:53], v[162:165], v[142:145], v[50:53]
	v_mfma_f32_16x16x32_bf16 v[54:57], v[166:169], v[142:145], v[54:57]
	v_mfma_f32_16x16x32_bf16 v[58:61], v[170:173], v[142:145], v[58:61]
	v_mfma_f32_16x16x32_bf16 v[62:65], v[174:177], v[142:145], v[62:65]
	s_waitcnt lgkmcnt(0)
	v_mfma_f32_16x16x32_bf16 v[2:5], v[178:181], v[146:149], v[2:5]
	v_mfma_f32_16x16x32_bf16 v[6:9], v[182:185], v[146:149], v[6:9]
	v_mfma_f32_16x16x32_bf16 v[10:13], v[186:189], v[146:149], v[10:13]
	v_mfma_f32_16x16x32_bf16 v[14:17], v[190:193], v[146:149], v[14:17]
	v_mfma_f32_16x16x32_bf16 v[18:21], v[178:181], v[150:153], v[18:21]
	v_mfma_f32_16x16x32_bf16 v[22:25], v[182:185], v[150:153], v[22:25]
	v_mfma_f32_16x16x32_bf16 v[26:29], v[186:189], v[150:153], v[26:29]
	v_mfma_f32_16x16x32_bf16 v[30:33], v[190:193], v[150:153], v[30:33]
	v_mfma_f32_16x16x32_bf16 v[34:37], v[178:181], v[154:157], v[34:37]
	v_mfma_f32_16x16x32_bf16 v[38:41], v[182:185], v[154:157], v[38:41]
	v_mfma_f32_16x16x32_bf16 v[42:45], v[186:189], v[154:157], v[42:45]
	v_mfma_f32_16x16x32_bf16 v[46:49], v[190:193], v[154:157], v[46:49]
	v_mfma_f32_16x16x32_bf16 v[50:53], v[178:181], v[158:161], v[50:53]
	v_mfma_f32_16x16x32_bf16 v[54:57], v[182:185], v[158:161], v[54:57]
	v_mfma_f32_16x16x32_bf16 v[58:61], v[186:189], v[158:161], v[58:61]
	v_mfma_f32_16x16x32_bf16 v[62:65], v[190:193], v[158:161], v[62:65]
	s_waitcnt vmcnt(6)
	s_barrier
	s_nop 7
	v_lshlrev_b32_e32 v206, 16, v98
	v_and_b32_e32 v207, 0xffff0000, v98
	v_lshlrev_b32_e32 v208, 16, v99
	v_and_b32_e32 v209, 0xffff0000, v99
	v_lshlrev_b32_e32 v210, 16, v66
	v_and_b32_e32 v211, 0xffff0000, v66
	v_lshlrev_b32_e32 v212, 16, v67
	v_and_b32_e32 v213, 0xffff0000, v67
	v_pk_fma_f32 v[210:211], v[2:3], v[206:207], v[210:211]
	v_pk_fma_f32 v[212:213], v[4:5], v[208:209], v[212:213]
	v_cvt_pk_bf16_f32 v66, v210, v211
	v_cvt_pk_bf16_f32 v67, v212, v213
	v_lshlrev_b32_e32 v206, 16, v100
	v_and_b32_e32 v207, 0xffff0000, v100
	v_lshlrev_b32_e32 v208, 16, v101
	v_and_b32_e32 v209, 0xffff0000, v101
	v_lshlrev_b32_e32 v210, 16, v68
	v_and_b32_e32 v211, 0xffff0000, v68
	v_lshlrev_b32_e32 v212, 16, v69
	v_and_b32_e32 v213, 0xffff0000, v69
	v_pk_fma_f32 v[210:211], v[6:7], v[206:207], v[210:211]
	v_pk_fma_f32 v[212:213], v[8:9], v[208:209], v[212:213]
	v_cvt_pk_bf16_f32 v68, v210, v211
	v_cvt_pk_bf16_f32 v69, v212, v213
	v_lshlrev_b32_e32 v206, 16, v102
	v_and_b32_e32 v207, 0xffff0000, v102
	v_lshlrev_b32_e32 v208, 16, v103
	v_and_b32_e32 v209, 0xffff0000, v103
	v_lshlrev_b32_e32 v210, 16, v70
	v_and_b32_e32 v211, 0xffff0000, v70
	v_lshlrev_b32_e32 v212, 16, v71
	v_and_b32_e32 v213, 0xffff0000, v71
	v_pk_fma_f32 v[210:211], v[10:11], v[206:207], v[210:211]
	v_pk_fma_f32 v[212:213], v[12:13], v[208:209], v[212:213]
	v_cvt_pk_bf16_f32 v70, v210, v211
	v_cvt_pk_bf16_f32 v71, v212, v213
	v_lshlrev_b32_e32 v206, 16, v104
	v_and_b32_e32 v207, 0xffff0000, v104
	v_lshlrev_b32_e32 v208, 16, v105
	v_and_b32_e32 v209, 0xffff0000, v105
	v_lshlrev_b32_e32 v210, 16, v72
	v_and_b32_e32 v211, 0xffff0000, v72
	v_lshlrev_b32_e32 v212, 16, v73
	v_and_b32_e32 v213, 0xffff0000, v73
	v_pk_fma_f32 v[210:211], v[14:15], v[206:207], v[210:211]
	v_pk_fma_f32 v[212:213], v[16:17], v[208:209], v[212:213]
	v_cvt_pk_bf16_f32 v72, v210, v211
	v_cvt_pk_bf16_f32 v73, v212, v213
	v_lshlrev_b32_e32 v206, 16, v106
	v_and_b32_e32 v207, 0xffff0000, v106
	v_lshlrev_b32_e32 v208, 16, v107
	v_and_b32_e32 v209, 0xffff0000, v107
	v_lshlrev_b32_e32 v210, 16, v74
	v_and_b32_e32 v211, 0xffff0000, v74
; #define LAS __attribute__((address_space(3)))
; __device__ __forceinline__ void branch_phase(LAS unsigned char* lds, const bf16_t* __restrict__ O, const bf16_t* __restrict__ Wb, const bf16_t* __restrict__ Gt, bf16_t* __restrict__ MG, int tg, int wv) {
;     ...
;         BR_LOAD(0, 0);
;         asm volatile("s_waitcnt vmcnt(0)" ::: "memory"); __syncthreads();
;         for (int j = 0; j < 4; ++j) {
;             u32x2 gv[4][4];
;             f32x4 acc[4][4];
; #pragma unroll
;             for (int m = 0; m < 4; ++m)
; #pragma unroll
;                 for (int n = 0; n < 4; ++n) acc[m][n] = (f32x4){0.f, 0.f, 0.f, 0.f};
;             for (int kc = 0; kc < 4; ++kc) {
;                 const int c = j * 4 + kc;
;                 if (c + 1 < 16) BR_LOAD(c + 1, (c + 1) & 1);
;                 if (kc == 3) {
;                     const bf16_t* gp = Gt + (size_t)(rt * 128 + wm * 64 + fr) * ZC + j * 1024 + ct * 256 + wn * 64 + 4 * fq;
; #pragma unroll
;                     for (int m = 0; m < 4; ++m)
; #pragma unroll
;                         for (int n = 0; n < 4; ++n) gv[m][n] = *(const u32x2*)(gp + (size_t)m * 16 * ZC + n * 16);
;                 }
;                 LAS const unsigned char* st = lds + (c & 1) * STG;
; #pragma unroll
;                 for (int k = 0; k < 2; ++k) {
;                     __builtin_amdgcn_sched_barrier(0);
;                     bf16x8 af[4], bfr[4];
; #pragma unroll
;                     for (int m = 0; m < 4; ++m) af[m] = *(LAS const bf16x8*)(st + aoff + m * 2048 + k * 1024);
; #pragma unroll
;                     for (int n = 0; n < 4; ++n) bfr[n] = *(LAS const bf16x8*)(st + boff + n * 2048 + k * 1024);
;     ...
; #pragma unroll
;             for (int m = 0; m < 4; ++m)
; #pragma unroll
;                 for (int n = 0; n < 4; ++n) { const u32x2 g = gv[m][n], sp = sum[m][n];
;                     const float s0_ = __builtin_bit_cast(float, sp.x << 16) + acc[m][n][0] * __builtin_bit_cast(float, g.x << 16), s1_ = __builtin_bit_cast(float, sp.x & 0xffff0000u) + acc[m][n][1] * __builtin_bit_cast(float, g.x & 0xffff0000u);
;                     const float s2_ = __builtin_bit_cast(float, sp.y << 16) + acc[m][n][2] * __builtin_bit_cast(float, g.y << 16), s3_ = __builtin_bit_cast(float, sp.y & 0xffff0000u) + acc[m][n][3] * __builtin_bit_cast(float, g.y & 0xffff0000u);
;                     sum[m][n] = (u32x2){cvtpk(s0_, s1_), cvtpk(s2_, s3_)}; }
	v_lshlrev_b32_e32 v212, 16, v75
	v_and_b32_e32 v213, 0xffff0000, v75
	v_pk_fma_f32 v[210:211], v[18:19], v[206:207], v[210:211]
	v_pk_fma_f32 v[212:213], v[20:21], v[208:209], v[212:213]
	v_cvt_pk_bf16_f32 v74, v210, v211
	v_cvt_pk_bf16_f32 v75, v212, v213
	v_lshlrev_b32_e32 v206, 16, v108
	v_and_b32_e32 v207, 0xffff0000, v108
	v_lshlrev_b32_e32 v208, 16, v109
	v_and_b32_e32 v209, 0xffff0000, v109
	v_lshlrev_b32_e32 v210, 16, v76
	v_and_b32_e32 v211, 0xffff0000, v76
	v_lshlrev_b32_e32 v212, 16, v77
	v_and_b32_e32 v213, 0xffff0000, v77
	v_pk_fma_f32 v[210:211], v[22:23], v[206:207], v[210:211]
	v_pk_fma_f32 v[212:213], v[24:25], v[208:209], v[212:213]
	v_cvt_pk_bf16_f32 v76, v210, v211
	v_cvt_pk_bf16_f32 v77, v212, v213
	v_lshlrev_b32_e32 v206, 16, v110
	v_and_b32_e32 v207, 0xffff0000, v110
	v_lshlrev_b32_e32 v208, 16, v111
	v_and_b32_e32 v209, 0xffff0000, v111
	v_lshlrev_b32_e32 v210, 16, v78
	v_and_b32_e32 v211, 0xffff0000, v78
	v_lshlrev_b32_e32 v212, 16, v79
	v_and_b32_e32 v213, 0xffff0000, v79
	v_pk_fma_f32 v[210:211], v[26:27], v[206:207], v[210:211]
	v_pk_fma_f32 v[212:213], v[28:29], v[208:209], v[212:213]
	v_cvt_pk_bf16_f32 v78, v210, v211
	v_cvt_pk_bf16_f32 v79, v212, v213
	v_lshlrev_b32_e32 v206, 16, v112
	v_and_b32_e32 v207, 0xffff0000, v112
	v_lshlrev_b32_e32 v208, 16, v113
	v_and_b32_e32 v209, 0xffff0000, v113
	v_lshlrev_b32_e32 v210, 16, v80
	v_and_b32_e32 v211, 0xffff0000, v80
	v_lshlrev_b32_e32 v212, 16, v81
	v_and_b32_e32 v213, 0xffff0000, v81
	v_pk_fma_f32 v[210:211], v[30:31], v[206:207], v[210:211]
	v_pk_fma_f32 v[212:213], v[32:33], v[208:209], v[212:213]
	v_cvt_pk_bf16_f32 v80, v210, v211
	v_cvt_pk_bf16_f32 v81, v212, v213
	v_lshlrev_b32_e32 v206, 16, v114
	v_and_b32_e32 v207, 0xffff0000, v114
	v_lshlrev_b32_e32 v208, 16, v115
	v_and_b32_e32 v209, 0xffff0000, v115
	v_lshlrev_b32_e32 v210, 16, v82
	v_and_b32_e32 v211, 0xffff0000, v82
	v_lshlrev_b32_e32 v212, 16, v83
	v_and_b32_e32 v213, 0xffff0000, v83
	v_pk_fma_f32 v[210:211], v[34:35], v[206:207], v[210:211]
	v_pk_fma_f32 v[212:213], v[36:37], v[208:209], v[212:213]
	v_cvt_pk_bf16_f32 v82, v210, v211
	v_cvt_pk_bf16_f32 v83, v212, v213
	v_lshlrev_b32_e32 v206, 16, v116
	v_and_b32_e32 v207, 0xffff0000, v116
	v_lshlrev_b32_e32 v208, 16, v117
	v_and_b32_e32 v209, 0xffff0000, v117
	v_lshlrev_b32_e32 v210, 16, v84
	v_and_b32_e32 v211, 0xffff0000, v84
	v_lshlrev_b32_e32 v212, 16, v85
	v_and_b32_e32 v213, 0xffff0000, v85
	v_pk_fma_f32 v[210:211], v[38:39], v[206:207], v[210:211]
	v_pk_fma_f32 v[212:213], v[40:41], v[208:209], v[212:213]
	v_cvt_pk_bf16_f32 v84, v210, v211
	v_cvt_pk_bf16_f32 v85, v212, v213
	v_lshlrev_b32_e32 v206, 16, v118
	v_and_b32_e32 v207, 0xffff0000, v118
	v_lshlrev_b32_e32 v208, 16, v119
	v_and_b32_e32 v209, 0xffff0000, v119
	v_lshlrev_b32_e32 v210, 16, v86
	v_and_b32_e32 v211, 0xffff0000, v86
	v_lshlrev_b32_e32 v212, 16, v87
	v_and_b32_e32 v213, 0xffff0000, v87
	v_pk_fma_f32 v[210:211], v[42:43], v[206:207], v[210:211]
	v_pk_fma_f32 v[212:213], v[44:45], v[208:209], v[212:213]
	v_cvt_pk_bf16_f32 v86, v210, v211
	v_cvt_pk_bf16_f32 v87, v212, v213
	v_lshlrev_b32_e32 v206, 16, v120
	v_and_b32_e32 v207, 0xffff0000, v120
	v_lshlrev_b32_e32 v208, 16, v121
	v_and_b32_e32 v209, 0xffff0000, v121
	v_lshlrev_b32_e32 v210, 16, v88
	v_and_b32_e32 v211, 0xffff0000, v88
	v_lshlrev_b32_e32 v212, 16, v89
	v_and_b32_e32 v213, 0xffff0000, v89
	v_pk_fma_f32 v[210:211], v[46:47], v[206:207], v[210:211]
	v_pk_fma_f32 v[212:213], v[48:49], v[208:209], v[212:213]
	v_cvt_pk_bf16_f32 v88, v210, v211
	v_cvt_pk_bf16_f32 v89, v212, v213
	v_lshlrev_b32_e32 v206, 16, v122
	v_and_b32_e32 v207, 0xffff0000, v122
	v_lshlrev_b32_e32 v208, 16, v123
	v_and_b32_e32 v209, 0xffff0000, v123
	v_lshlrev_b32_e32 v210, 16, v90
	v_and_b32_e32 v211, 0xffff0000, v90
	v_lshlrev_b32_e32 v212, 16, v91
	v_and_b32_e32 v213, 0xffff0000, v91
	v_pk_fma_f32 v[210:211], v[50:51], v[206:207], v[210:211]
	v_pk_fma_f32 v[212:213], v[52:53], v[208:209], v[212:213]
	v_cvt_pk_bf16_f32 v90, v210, v211
	v_cvt_pk_bf16_f32 v91, v212, v213
	v_lshlrev_b32_e32 v206, 16, v124
	v_and_b32_e32 v207, 0xffff0000, v124
	v_lshlrev_b32_e32 v208, 16, v125
	v_and_b32_e32 v209, 0xffff0000, v125
	v_lshlrev_b32_e32 v210, 16, v92
	v_and_b32_e32 v211, 0xffff0000, v92
	v_lshlrev_b32_e32 v212, 16, v93
	v_and_b32_e32 v213, 0xffff0000, v93
	v_pk_fma_f32 v[210:211], v[54:55], v[206:207], v[210:211]
	v_pk_fma_f32 v[212:213], v[56:57], v[208:209], v[212:213]
	v_cvt_pk_bf16_f32 v92, v210, v211
	v_cvt_pk_bf16_f32 v93, v212, v213
	v_lshlrev_b32_e32 v206, 16, v126
	v_and_b32_e32 v207, 0xffff0000, v126
	v_lshlrev_b32_e32 v208, 16, v127
	v_and_b32_e32 v209, 0xffff0000, v127
	v_lshlrev_b32_e32 v210, 16, v94
	v_and_b32_e32 v211, 0xffff0000, v94
	v_lshlrev_b32_e32 v212, 16, v95
	v_and_b32_e32 v213, 0xffff0000, v95
	v_pk_fma_f32 v[210:211], v[58:59], v[206:207], v[210:211]
	v_pk_fma_f32 v[212:213], v[60:61], v[208:209], v[212:213]
	v_cvt_pk_bf16_f32 v94, v210, v211
	v_cvt_pk_bf16_f32 v95, v212, v213
	v_lshlrev_b32_e32 v206, 16, v128
	v_and_b32_e32 v207, 0xffff0000, v128
	v_lshlrev_b32_e32 v208, 16, v129
	v_and_b32_e32 v209, 0xffff0000, v129
	v_lshlrev_b32_e32 v210, 16, v96
	v_and_b32_e32 v211, 0xffff0000, v96
	v_lshlrev_b32_e32 v212, 16, v97
	v_and_b32_e32 v213, 0xffff0000, v97
	v_pk_fma_f32 v[210:211], v[62:63], v[206:207], v[210:211]
	v_pk_fma_f32 v[212:213], v[64:65], v[208:209], v[212:213]
	v_cvt_pk_bf16_f32 v96, v210, v211
	v_cvt_pk_bf16_f32 v97, v212, v213
	s_add_u32 s66, s64, 0x300
	s_addc_u32 s67, s65, 0
	s_add_u32 s70, s68, 0x80100
	s_addc_u32 s71, s69, 0
	s_add_u32 s72, s70, 0x10000
	s_addc_u32 s73, s71, 0
	s_mov_b32 m0, s82
	s_nop 0
	global_load_lds_dwordx4 v197, s[66:67]
	s_add_i32 m0, s82, 0x2000
	s_nop 0
	global_load_lds_dwordx4 v198, s[66:67]
	s_add_i32 m0, s82, 0x4000
	s_nop 0
	global_load_lds_dwordx4 v199, s[70:71]
	s_add_i32 m0, s82, 0x6000
	s_nop 0
	global_load_lds_dwordx4 v200, s[70:71]
	s_mov_b32 m0, s85
	s_nop 0
	global_load_lds_dwordx4 v199, s[72:73]
	s_add_i32 m0, s85, 0x2000
	s_nop 0
	global_load_lds_dwordx4 v200, s[72:73]
	ds_read_b128 v[130:133], v215 offset:0
	ds_read_b128 v[134:137], v215 offset:2048
	ds_read_b128 v[138:141], v215 offset:4096
	ds_read_b128 v[142:145], v215 offset:6144
	ds_read_b128 v[162:165], v218 offset:0
	ds_read_b128 v[166:169], v218 offset:2048
	ds_read_b128 v[170:173], v218 offset:4096
	ds_read_b128 v[174:177], v218 offset:6144
	ds_read_b128 v[146:149], v215 offset:1024
	ds_read_b128 v[150:153], v215 offset:3072
	ds_read_b128 v[154:157], v215 offset:5120
	ds_read_b128 v[158:161], v215 offset:7168
	ds_read_b128 v[178:181], v218 offset:1024
	ds_read_b128 v[182:185], v218 offset:3072
	ds_read_b128 v[186:189], v218 offset:5120
	ds_read_b128 v[190:193], v218 offset:7168
	s_waitcnt lgkmcnt(8)
; #define LAS __attribute__((address_space(3)))
; __device__ __forceinline__ void branch_phase(LAS unsigned char* lds, const bf16_t* __restrict__ O, const bf16_t* __restrict__ Wb, const bf16_t* __restrict__ Gt, bf16_t* __restrict__ MG, int tg, int wv) {
;     ...
;             for (int kc = 0; kc < 4; ++kc) {
;                 const int c = j * 4 + kc;
;                 if (c + 1 < 16) BR_LOAD(c + 1, (c + 1) & 1);
;                 if (kc == 3) {
;                     const bf16_t* gp = Gt + (size_t)(rt * 128 + wm * 64 + fr) * ZC + j * 1024 + ct * 256 + wn * 64 + 4 * fq;
; #pragma unroll
;                     for (int m = 0; m < 4; ++m)
; #pragma unroll
;                         for (int n = 0; n < 4; ++n) gv[m][n] = *(const u32x2*)(gp + (size_t)m * 16 * ZC + n * 16);
;                 }
;                 LAS const unsigned char* st = lds + (c & 1) * STG;
; #pragma unroll
;                 for (int k = 0; k < 2; ++k) {
;                     __builtin_amdgcn_sched_barrier(0);
;                     bf16x8 af[4], bfr[4];
; #pragma unroll
;                     for (int m = 0; m < 4; ++m) af[m] = *(LAS const bf16x8*)(st + aoff + m * 2048 + k * 1024);
; #pragma unroll
;                     for (int n = 0; n < 4; ++n) bfr[n] = *(LAS const bf16x8*)(st + boff + n * 2048 + k * 1024);
; #pragma unroll
;                     for (int m = 0; m < 4; ++m)
; #pragma unroll
;                         for (int n = 0; n < 4; ++n) acc[m][n] = __builtin_amdgcn_mfma_f32_16x16x32_bf16(bfr[n], af[m], acc[m][n], 0, 0, 0);
;                 }
;                 asm volatile("s_waitcnt vmcnt(0)" ::: "memory"); __syncthreads();
;             }
	v_mfma_f32_16x16x32_bf16 v[2:5], v[162:165], v[130:133], 0
	v_mfma_f32_16x16x32_bf16 v[6:9], v[166:169], v[130:133], 0
	v_mfma_f32_16x16x32_bf16 v[10:13], v[170:173], v[130:133], 0
	v_mfma_f32_16x16x32_bf16 v[14:17], v[174:177], v[130:133], 0
	v_mfma_f32_16x16x32_bf16 v[18:21], v[162:165], v[134:137], 0
	v_mfma_f32_16x16x32_bf16 v[22:25], v[166:169], v[134:137], 0
	v_mfma_f32_16x16x32_bf16 v[26:29], v[170:173], v[134:137], 0
	v_mfma_f32_16x16x32_bf16 v[30:33], v[174:177], v[134:137], 0
	v_mfma_f32_16x16x32_bf16 v[34:37], v[162:165], v[138:141], 0
	v_mfma_f32_16x16x32_bf16 v[38:41], v[166:169], v[138:141], 0
	v_mfma_f32_16x16x32_bf16 v[42:45], v[170:173], v[138:141], 0
	v_mfma_f32_16x16x32_bf16 v[46:49], v[174:177], v[138:141], 0
	v_mfma_f32_16x16x32_bf16 v[50:53], v[162:165], v[142:145], 0
	v_mfma_f32_16x16x32_bf16 v[54:57], v[166:169], v[142:145], 0
	v_mfma_f32_16x16x32_bf16 v[58:61], v[170:173], v[142:145], 0
	v_mfma_f32_16x16x32_bf16 v[62:65], v[174:177], v[142:145], 0
	s_waitcnt lgkmcnt(0)
	v_mfma_f32_16x16x32_bf16 v[2:5], v[178:181], v[146:149], v[2:5]
	v_mfma_f32_16x16x32_bf16 v[6:9], v[182:185], v[146:149], v[6:9]
	v_mfma_f32_16x16x32_bf16 v[10:13], v[186:189], v[146:149], v[10:13]
	v_mfma_f32_16x16x32_bf16 v[14:17], v[190:193], v[146:149], v[14:17]
	v_mfma_f32_16x16x32_bf16 v[18:21], v[178:181], v[150:153], v[18:21]
	v_mfma_f32_16x16x32_bf16 v[22:25], v[182:185], v[150:153], v[22:25]
	v_mfma_f32_16x16x32_bf16 v[26:29], v[186:189], v[150:153], v[26:29]
	v_mfma_f32_16x16x32_bf16 v[30:33], v[190:193], v[150:153], v[30:33]
	v_mfma_f32_16x16x32_bf16 v[34:37], v[178:181], v[154:157], v[34:37]
	v_mfma_f32_16x16x32_bf16 v[38:41], v[182:185], v[154:157], v[38:41]
	v_mfma_f32_16x16x32_bf16 v[42:45], v[186:189], v[154:157], v[42:45]
	v_mfma_f32_16x16x32_bf16 v[46:49], v[190:193], v[154:157], v[46:49]
	v_mfma_f32_16x16x32_bf16 v[50:53], v[178:181], v[158:161], v[50:53]
	v_mfma_f32_16x16x32_bf16 v[54:57], v[182:185], v[158:161], v[54:57]
	v_mfma_f32_16x16x32_bf16 v[58:61], v[186:189], v[158:161], v[58:61]
	v_mfma_f32_16x16x32_bf16 v[62:65], v[190:193], v[158:161], v[62:65]
	s_waitcnt vmcnt(6)
	s_barrier
	s_add_u32 s66, s64, 0x380
	s_addc_u32 s67, s65, 0
	s_add_u32 s70, s68, 0x80180
	s_addc_u32 s71, s69, 0
	s_add_u32 s72, s70, 0x10000
	s_addc_u32 s73, s71, 0
	s_mov_b32 m0, s83
	s_nop 0
	global_load_lds_dwordx4 v197, s[66:67]
	s_add_i32 m0, s83, 0x2000
	s_nop 0
	global_load_lds_dwordx4 v198, s[66:67]
	s_add_i32 m0, s83, 0x4000
	s_nop 0
	global_load_lds_dwordx4 v199, s[70:71]
	s_add_i32 m0, s83, 0x6000
	s_nop 0
	global_load_lds_dwordx4 v200, s[70:71]
	s_mov_b32 m0, s60
	s_nop 0
	global_load_lds_dwordx4 v199, s[72:73]
	s_add_i32 m0, s60, 0x2000
	s_nop 0
	global_load_lds_dwordx4 v200, s[72:73]
	s_add_u32 s80, s74, 0x800
	s_addc_u32 s81, s75, 0
	global_load_dwordx4 v[98:101], v204, s[80:81] offset:0
	global_load_dwordx4 v[102:105], v204, s[80:81] offset:64
	s_add_u32 s80, s80, 0x20000
	s_addc_u32 s81, s81, 0
	global_load_dwordx4 v[106:109], v204, s[80:81] offset:0
	global_load_dwordx4 v[110:113], v204, s[80:81] offset:64
	s_add_u32 s80, s80, 0x20000
	s_addc_u32 s81, s81, 0
	global_load_dwordx4 v[114:117], v204, s[80:81] offset:0
	global_load_dwordx4 v[118:121], v204, s[80:81] offset:64
	s_add_u32 s80, s80, 0x20000
	s_addc_u32 s81, s81, 0
	global_load_dwordx4 v[122:125], v204, s[80:81] offset:0
	global_load_dwordx4 v[126:129], v204, s[80:81] offset:64
	ds_read_b128 v[130:133], v216 offset:0
	ds_read_b128 v[134:137], v216 offset:2048
	ds_read_b128 v[138:141], v216 offset:4096
	ds_read_b128 v[142:145], v216 offset:6144
	ds_read_b128 v[162:165], v219 offset:0
	ds_read_b128 v[166:169], v219 offset:2048
	ds_read_b128 v[170:173], v219 offset:4096
	ds_read_b128 v[174:177], v219 offset:6144
	ds_read_b128 v[146:149], v216 offset:1024
	ds_read_b128 v[150:153], v216 offset:3072
	ds_read_b128 v[154:157], v216 offset:5120
	ds_read_b128 v[158:161], v216 offset:7168
	ds_read_b128 v[178:181], v219 offset:1024
	ds_read_b128 v[182:185], v219 offset:3072
	ds_read_b128 v[186:189], v219 offset:5120
	ds_read_b128 v[190:193], v219 offset:7168
	s_waitcnt lgkmcnt(8)
	v_mfma_f32_16x16x32_bf16 v[2:5], v[162:165], v[130:133], v[2:5]
	v_mfma_f32_16x16x32_bf16 v[6:9], v[166:169], v[130:133], v[6:9]
	v_mfma_f32_16x16x32_bf16 v[10:13], v[170:173], v[130:133], v[10:13]
	v_mfma_f32_16x16x32_bf16 v[14:17], v[174:177], v[130:133], v[14:17]
	v_mfma_f32_16x16x32_bf16 v[18:21], v[162:165], v[134:137], v[18:21]
	v_mfma_f32_16x16x32_bf16 v[22:25], v[166:169], v[134:137], v[22:25]
	v_mfma_f32_16x16x32_bf16 v[26:29], v[170:173], v[134:137], v[26:29]
	v_mfma_f32_16x16x32_bf16 v[30:33], v[174:177], v[134:137], v[30:33]
	v_mfma_f32_16x16x32_bf16 v[34:37], v[162:165], v[138:141], v[34:37]
	v_mfma_f32_16x16x32_bf16 v[38:41], v[166:169], v[138:141], v[38:41]
	v_mfma_f32_16x16x32_bf16 v[42:45], v[170:173], v[138:141], v[42:45]
	v_mfma_f32_16x16x32_bf16 v[46:49], v[174:177], v[138:141], v[46:49]
	v_mfma_f32_16x16x32_bf16 v[50:53], v[162:165], v[142:145], v[50:53]
	v_mfma_f32_16x16x32_bf16 v[54:57], v[166:169], v[142:145], v[54:57]
	v_mfma_f32_16x16x32_bf16 v[58:61], v[170:173], v[142:145], v[58:61]
	v_mfma_f32_16x16x32_bf16 v[62:65], v[174:177], v[142:145], v[62:65]
	s_waitcnt lgkmcnt(0)
	v_mfma_f32_16x16x32_bf16 v[2:5], v[178:181], v[146:149], v[2:5]
	v_mfma_f32_16x16x32_bf16 v[6:9], v[182:185], v[146:149], v[6:9]
	v_mfma_f32_16x16x32_bf16 v[10:13], v[186:189], v[146:149], v[10:13]
	v_mfma_f32_16x16x32_bf16 v[14:17], v[190:193], v[146:149], v[14:17]
	v_mfma_f32_16x16x32_bf16 v[18:21], v[178:181], v[150:153], v[18:21]
	v_mfma_f32_16x16x32_bf16 v[22:25], v[182:185], v[150:153], v[22:25]
	v_mfma_f32_16x16x32_bf16 v[26:29], v[186:189], v[150:153], v[26:29]
	v_mfma_f32_16x16x32_bf16 v[30:33], v[190:193], v[150:153], v[30:33]
	v_mfma_f32_16x16x32_bf16 v[34:37], v[178:181], v[154:157], v[34:37]
	v_mfma_f32_16x16x32_bf16 v[38:41], v[182:185], v[154:157], v[38:41]
	v_mfma_f32_16x16x32_bf16 v[42:45], v[186:189], v[154:157], v[42:45]
	v_mfma_f32_16x16x32_bf16 v[46:49], v[190:193], v[154:157], v[46:49]
	v_mfma_f32_16x16x32_bf16 v[50:53], v[178:181], v[158:161], v[50:53]
	v_mfma_f32_16x16x32_bf16 v[54:57], v[182:185], v[158:161], v[54:57]
	v_mfma_f32_16x16x32_bf16 v[58:61], v[186:189], v[158:161], v[58:61]
	v_mfma_f32_16x16x32_bf16 v[62:65], v[190:193], v[158:161], v[62:65]
	s_waitcnt vmcnt(14)
	s_barrier
; #define LAS __attribute__((address_space(3)))
; __device__ __forceinline__ void branch_phase(LAS unsigned char* lds, const bf16_t* __restrict__ O, const bf16_t* __restrict__ Wb, const bf16_t* __restrict__ Gt, bf16_t* __restrict__ MG, int tg, int wv) {
;     ...
;             for (int kc = 0; kc < 4; ++kc) {
;                 const int c = j * 4 + kc;
;                 if (c + 1 < 16) BR_LOAD(c + 1, (c + 1) & 1);
;                 if (kc == 3) {
;                     const bf16_t* gp = Gt + (size_t)(rt * 128 + wm * 64 + fr) * ZC + j * 1024 + ct * 256 + wn * 64 + 4 * fq;
; #pragma unroll
;                     for (int m = 0; m < 4; ++m)
; #pragma unroll
;                         for (int n = 0; n < 4; ++n) gv[m][n] = *(const u32x2*)(gp + (size_t)m * 16 * ZC + n * 16);
;                 }
;                 LAS const unsigned char* st = lds + (c & 1) * STG;
; #pragma unroll
;                 for (int k = 0; k < 2; ++k) {
;                     __builtin_amdgcn_sched_barrier(0);
;                     bf16x8 af[4], bfr[4];
; #pragma unroll
;                     for (int m = 0; m < 4; ++m) af[m] = *(LAS const bf16x8*)(st + aoff + m * 2048 + k * 1024);
; #pragma unroll
;                     for (int n = 0; n < 4; ++n) bfr[n] = *(LAS const bf16x8*)(st + boff + n * 2048 + k * 1024);
; #pragma unroll
;                     for (int m = 0; m < 4; ++m)
; #pragma unroll
;                         for (int n = 0; n < 4; ++n) acc[m][n] = __builtin_amdgcn_mfma_f32_16x16x32_bf16(bfr[n], af[m], acc[m][n], 0, 0, 0);
;                 }
;                 asm volatile("s_waitcnt vmcnt(0)" ::: "memory"); __syncthreads();
;             }
	s_add_u32 s66, s64, 0x400
	s_addc_u32 s67, s65, 0
	s_add_u32 s70, s68, 0x100000
	s_addc_u32 s71, s69, 0
	s_add_u32 s72, s70, 0x10000
	s_addc_u32 s73, s71, 0
	s_mov_b32 m0, s84
	s_nop 0
	global_load_lds_dwordx4 v197, s[66:67]
	s_add_i32 m0, s84, 0x2000
	s_nop 0
	global_load_lds_dwordx4 v198, s[66:67]
	s_add_i32 m0, s84, 0x4000
	s_nop 0
	global_load_lds_dwordx4 v199, s[70:71]
	s_add_i32 m0, s84, 0x6000
	s_nop 0
	global_load_lds_dwordx4 v200, s[70:71]
	s_mov_b32 m0, s61
	s_nop 0
	global_load_lds_dwordx4 v199, s[72:73]
	s_add_i32 m0, s61, 0x2000
	s_nop 0
	global_load_lds_dwordx4 v200, s[72:73]
	ds_read_b128 v[130:133], v214 offset:0
	ds_read_b128 v[134:137], v214 offset:2048
	ds_read_b128 v[138:141], v214 offset:4096
	ds_read_b128 v[142:145], v214 offset:6144
	ds_read_b128 v[162:165], v217 offset:0
	ds_read_b128 v[166:169], v217 offset:2048
	ds_read_b128 v[170:173], v217 offset:4096
	ds_read_b128 v[174:177], v217 offset:6144
	ds_read_b128 v[146:149], v214 offset:1024
	ds_read_b128 v[150:153], v214 offset:3072
	ds_read_b128 v[154:157], v214 offset:5120
	ds_read_b128 v[158:161], v214 offset:7168
	ds_read_b128 v[178:181], v217 offset:1024
	ds_read_b128 v[182:185], v217 offset:3072
	ds_read_b128 v[186:189], v217 offset:5120
	ds_read_b128 v[190:193], v217 offset:7168
	s_waitcnt lgkmcnt(8)
	v_mfma_f32_16x16x32_bf16 v[2:5], v[162:165], v[130:133], v[2:5]
	v_mfma_f32_16x16x32_bf16 v[6:9], v[166:169], v[130:133], v[6:9]
	v_mfma_f32_16x16x32_bf16 v[10:13], v[170:173], v[130:133], v[10:13]
	v_mfma_f32_16x16x32_bf16 v[14:17], v[174:177], v[130:133], v[14:17]
	v_mfma_f32_16x16x32_bf16 v[18:21], v[162:165], v[134:137], v[18:21]
	v_mfma_f32_16x16x32_bf16 v[22:25], v[166:169], v[134:137], v[22:25]
	v_mfma_f32_16x16x32_bf16 v[26:29], v[170:173], v[134:137], v[26:29]
	v_mfma_f32_16x16x32_bf16 v[30:33], v[174:177], v[134:137], v[30:33]
	v_mfma_f32_16x16x32_bf16 v[34:37], v[162:165], v[138:141], v[34:37]
	v_mfma_f32_16x16x32_bf16 v[38:41], v[166:169], v[138:141], v[38:41]
	v_mfma_f32_16x16x32_bf16 v[42:45], v[170:173], v[138:141], v[42:45]
	v_mfma_f32_16x16x32_bf16 v[46:49], v[174:177], v[138:141], v[46:49]
	v_mfma_f32_16x16x32_bf16 v[50:53], v[162:165], v[142:145], v[50:53]
	v_mfma_f32_16x16x32_bf16 v[54:57], v[166:169], v[142:145], v[54:57]
	v_mfma_f32_16x16x32_bf16 v[58:61], v[170:173], v[142:145], v[58:61]
	v_mfma_f32_16x16x32_bf16 v[62:65], v[174:177], v[142:145], v[62:65]
	s_waitcnt lgkmcnt(0)
	v_mfma_f32_16x16x32_bf16 v[2:5], v[178:181], v[146:149], v[2:5]
	v_mfma_f32_16x16x32_bf16 v[6:9], v[182:185], v[146:149], v[6:9]
	v_mfma_f32_16x16x32_bf16 v[10:13], v[186:189], v[146:149], v[10:13]
	v_mfma_f32_16x16x32_bf16 v[14:17], v[190:193], v[146:149], v[14:17]
	v_mfma_f32_16x16x32_bf16 v[18:21], v[178:181], v[150:153], v[18:21]
	v_mfma_f32_16x16x32_bf16 v[22:25], v[182:185], v[150:153], v[22:25]
	v_mfma_f32_16x16x32_bf16 v[26:29], v[186:189], v[150:153], v[26:29]
	v_mfma_f32_16x16x32_bf16 v[30:33], v[190:193], v[150:153], v[30:33]
	v_mfma_f32_16x16x32_bf16 v[34:37], v[178:181], v[154:157], v[34:37]
	v_mfma_f32_16x16x32_bf16 v[38:41], v[182:185], v[154:157], v[38:41]
	v_mfma_f32_16x16x32_bf16 v[42:45], v[186:189], v[154:157], v[42:45]
	v_mfma_f32_16x16x32_bf16 v[46:49], v[190:193], v[154:157], v[46:49]
	v_mfma_f32_16x16x32_bf16 v[50:53], v[178:181], v[158:161], v[50:53]
	v_mfma_f32_16x16x32_bf16 v[54:57], v[182:185], v[158:161], v[54:57]
	v_mfma_f32_16x16x32_bf16 v[58:61], v[186:189], v[158:161], v[58:61]
	v_mfma_f32_16x16x32_bf16 v[62:65], v[190:193], v[158:161], v[62:65]
	s_waitcnt vmcnt(14)
	s_barrier
	s_add_u32 s66, s64, 0x480
	s_addc_u32 s67, s65, 0
	s_add_u32 s70, s68, 0x100080
	s_addc_u32 s71, s69, 0
	s_add_u32 s72, s70, 0x10000
	s_addc_u32 s73, s71, 0
	s_mov_b32 m0, s82
	s_nop 0
	global_load_lds_dwordx4 v197, s[66:67]
	s_add_i32 m0, s82, 0x2000
	s_nop 0
	global_load_lds_dwordx4 v198, s[66:67]
	s_add_i32 m0, s82, 0x4000
	s_nop 0
	global_load_lds_dwordx4 v199, s[70:71]
	s_add_i32 m0, s82, 0x6000
	s_nop 0
	global_load_lds_dwordx4 v200, s[70:71]
	s_mov_b32 m0, s85
	s_nop 0
	global_load_lds_dwordx4 v199, s[72:73]
	s_add_i32 m0, s85, 0x2000
	s_nop 0
	global_load_lds_dwordx4 v200, s[72:73]
	ds_read_b128 v[130:133], v215 offset:0
	ds_read_b128 v[134:137], v215 offset:2048
	ds_read_b128 v[138:141], v215 offset:4096
	ds_read_b128 v[142:145], v215 offset:6144
	ds_read_b128 v[162:165], v218 offset:0
	ds_read_b128 v[166:169], v218 offset:2048
	ds_read_b128 v[170:173], v218 offset:4096
	ds_read_b128 v[174:177], v218 offset:6144
	ds_read_b128 v[146:149], v215 offset:1024
	ds_read_b128 v[150:153], v215 offset:3072
	ds_read_b128 v[154:157], v215 offset:5120
	ds_read_b128 v[158:161], v215 offset:7168
	ds_read_b128 v[178:181], v218 offset:1024
	ds_read_b128 v[182:185], v218 offset:3072
	ds_read_b128 v[186:189], v218 offset:5120
	ds_read_b128 v[190:193], v218 offset:7168
	s_waitcnt lgkmcnt(8)
	v_mfma_f32_16x16x32_bf16 v[2:5], v[162:165], v[130:133], v[2:5]
	v_mfma_f32_16x16x32_bf16 v[6:9], v[166:169], v[130:133], v[6:9]
	v_mfma_f32_16x16x32_bf16 v[10:13], v[170:173], v[130:133], v[10:13]
	v_mfma_f32_16x16x32_bf16 v[14:17], v[174:177], v[130:133], v[14:17]
	v_mfma_f32_16x16x32_bf16 v[18:21], v[162:165], v[134:137], v[18:21]
	v_mfma_f32_16x16x32_bf16 v[22:25], v[166:169], v[134:137], v[22:25]
	v_mfma_f32_16x16x32_bf16 v[26:29], v[170:173], v[134:137], v[26:29]
	v_mfma_f32_16x16x32_bf16 v[30:33], v[174:177], v[134:137], v[30:33]
	v_mfma_f32_16x16x32_bf16 v[34:37], v[162:165], v[138:141], v[34:37]
	v_mfma_f32_16x16x32_bf16 v[38:41], v[166:169], v[138:141], v[38:41]
	v_mfma_f32_16x16x32_bf16 v[42:45], v[170:173], v[138:141], v[42:45]
	v_mfma_f32_16x16x32_bf16 v[46:49], v[174:177], v[138:141], v[46:49]
	v_mfma_f32_16x16x32_bf16 v[50:53], v[162:165], v[142:145], v[50:53]
	v_mfma_f32_16x16x32_bf16 v[54:57], v[166:169], v[142:145], v[54:57]
	v_mfma_f32_16x16x32_bf16 v[58:61], v[170:173], v[142:145], v[58:61]
	v_mfma_f32_16x16x32_bf16 v[62:65], v[174:177], v[142:145], v[62:65]
	s_waitcnt lgkmcnt(0)
; __device__ __forceinline__ unsigned cvtpk(float lo, float hi) { f32x2 v = {lo, hi}; bf16x2_t b = __builtin_convertvector(v, bf16x2_t); return __builtin_bit_cast(unsigned, b); }
; __device__ __forceinline__ void branch_phase(LAS unsigned char* lds, const bf16_t* __restrict__ O, const bf16_t* __restrict__ Wb, const bf16_t* __restrict__ Gt, bf16_t* __restrict__ MG, int tg, int wv) {
;     ...
;                     for (int m = 0; m < 4; ++m)
; #pragma unroll
;                         for (int n = 0; n < 4; ++n) acc[m][n] = __builtin_amdgcn_mfma_f32_16x16x32_bf16(bfr[n], af[m], acc[m][n], 0, 0, 0);
;                 }
;                 asm volatile("s_waitcnt vmcnt(0)" ::: "memory"); __syncthreads();
;             }
; #pragma unroll
;             for (int m = 0; m < 4; ++m)
; #pragma unroll
;                 for (int n = 0; n < 4; ++n) { const u32x2 g = gv[m][n], sp = sum[m][n];
;                     const float s0_ = __builtin_bit_cast(float, sp.x << 16) + acc[m][n][0] * __builtin_bit_cast(float, g.x << 16), s1_ = __builtin_bit_cast(float, sp.x & 0xffff0000u) + acc[m][n][1] * __builtin_bit_cast(float, g.x & 0xffff0000u);
;                     const float s2_ = __builtin_bit_cast(float, sp.y << 16) + acc[m][n][2] * __builtin_bit_cast(float, g.y << 16), s3_ = __builtin_bit_cast(float, sp.y & 0xffff0000u) + acc[m][n][3] * __builtin_bit_cast(float, g.y & 0xffff0000u);
;                     sum[m][n] = (u32x2){cvtpk(s0_, s1_), cvtpk(s2_, s3_)}; }
	v_mfma_f32_16x16x32_bf16 v[2:5], v[178:181], v[146:149], v[2:5]
	v_mfma_f32_16x16x32_bf16 v[6:9], v[182:185], v[146:149], v[6:9]
	v_mfma_f32_16x16x32_bf16 v[10:13], v[186:189], v[146:149], v[10:13]
	v_mfma_f32_16x16x32_bf16 v[14:17], v[190:193], v[146:149], v[14:17]
	v_mfma_f32_16x16x32_bf16 v[18:21], v[178:181], v[150:153], v[18:21]
	v_mfma_f32_16x16x32_bf16 v[22:25], v[182:185], v[150:153], v[22:25]
	v_mfma_f32_16x16x32_bf16 v[26:29], v[186:189], v[150:153], v[26:29]
	v_mfma_f32_16x16x32_bf16 v[30:33], v[190:193], v[150:153], v[30:33]
	v_mfma_f32_16x16x32_bf16 v[34:37], v[178:181], v[154:157], v[34:37]
	v_mfma_f32_16x16x32_bf16 v[38:41], v[182:185], v[154:157], v[38:41]
	v_mfma_f32_16x16x32_bf16 v[42:45], v[186:189], v[154:157], v[42:45]
	v_mfma_f32_16x16x32_bf16 v[46:49], v[190:193], v[154:157], v[46:49]
	v_mfma_f32_16x16x32_bf16 v[50:53], v[178:181], v[158:161], v[50:53]
	v_mfma_f32_16x16x32_bf16 v[54:57], v[182:185], v[158:161], v[54:57]
	v_mfma_f32_16x16x32_bf16 v[58:61], v[186:189], v[158:161], v[58:61]
	v_mfma_f32_16x16x32_bf16 v[62:65], v[190:193], v[158:161], v[62:65]
	s_waitcnt vmcnt(6)
	s_barrier
	s_nop 7
	v_lshlrev_b32_e32 v206, 16, v98
	v_and_b32_e32 v207, 0xffff0000, v98
	v_lshlrev_b32_e32 v208, 16, v99
	v_and_b32_e32 v209, 0xffff0000, v99
	v_lshlrev_b32_e32 v210, 16, v66
	v_and_b32_e32 v211, 0xffff0000, v66
	v_lshlrev_b32_e32 v212, 16, v67
	v_and_b32_e32 v213, 0xffff0000, v67
	v_pk_fma_f32 v[210:211], v[2:3], v[206:207], v[210:211]
	v_pk_fma_f32 v[212:213], v[4:5], v[208:209], v[212:213]
	v_cvt_pk_bf16_f32 v66, v210, v211
	v_cvt_pk_bf16_f32 v67, v212, v213
	v_lshlrev_b32_e32 v206, 16, v100
	v_and_b32_e32 v207, 0xffff0000, v100
	v_lshlrev_b32_e32 v208, 16, v101
	v_and_b32_e32 v209, 0xffff0000, v101
	v_lshlrev_b32_e32 v210, 16, v68
	v_and_b32_e32 v211, 0xffff0000, v68
	v_lshlrev_b32_e32 v212, 16, v69
	v_and_b32_e32 v213, 0xffff0000, v69
	v_pk_fma_f32 v[210:211], v[6:7], v[206:207], v[210:211]
	v_pk_fma_f32 v[212:213], v[8:9], v[208:209], v[212:213]
	v_cvt_pk_bf16_f32 v68, v210, v211
	v_cvt_pk_bf16_f32 v69, v212, v213
	v_lshlrev_b32_e32 v206, 16, v102
	v_and_b32_e32 v207, 0xffff0000, v102
	v_lshlrev_b32_e32 v208, 16, v103
	v_and_b32_e32 v209, 0xffff0000, v103
	v_lshlrev_b32_e32 v210, 16, v70
	v_and_b32_e32 v211, 0xffff0000, v70
	v_lshlrev_b32_e32 v212, 16, v71
	v_and_b32_e32 v213, 0xffff0000, v71
	v_pk_fma_f32 v[210:211], v[10:11], v[206:207], v[210:211]
	v_pk_fma_f32 v[212:213], v[12:13], v[208:209], v[212:213]
	v_cvt_pk_bf16_f32 v70, v210, v211
	v_cvt_pk_bf16_f32 v71, v212, v213
	v_lshlrev_b32_e32 v206, 16, v104
	v_and_b32_e32 v207, 0xffff0000, v104
	v_lshlrev_b32_e32 v208, 16, v105
	v_and_b32_e32 v209, 0xffff0000, v105
	v_lshlrev_b32_e32 v210, 16, v72
	v_and_b32_e32 v211, 0xffff0000, v72
	v_lshlrev_b32_e32 v212, 16, v73
	v_and_b32_e32 v213, 0xffff0000, v73
	v_pk_fma_f32 v[210:211], v[14:15], v[206:207], v[210:211]
	v_pk_fma_f32 v[212:213], v[16:17], v[208:209], v[212:213]
	v_cvt_pk_bf16_f32 v72, v210, v211
	v_cvt_pk_bf16_f32 v73, v212, v213
	v_lshlrev_b32_e32 v206, 16, v106
	v_and_b32_e32 v207, 0xffff0000, v106
	v_lshlrev_b32_e32 v208, 16, v107
	v_and_b32_e32 v209, 0xffff0000, v107
	v_lshlrev_b32_e32 v210, 16, v74
	v_and_b32_e32 v211, 0xffff0000, v74
	v_lshlrev_b32_e32 v212, 16, v75
	v_and_b32_e32 v213, 0xffff0000, v75
	v_pk_fma_f32 v[210:211], v[18:19], v[206:207], v[210:211]
	v_pk_fma_f32 v[212:213], v[20:21], v[208:209], v[212:213]
	v_cvt_pk_bf16_f32 v74, v210, v211
	v_cvt_pk_bf16_f32 v75, v212, v213
	v_lshlrev_b32_e32 v206, 16, v108
	v_and_b32_e32 v207, 0xffff0000, v108
	v_lshlrev_b32_e32 v208, 16, v109
	v_and_b32_e32 v209, 0xffff0000, v109
	v_lshlrev_b32_e32 v210, 16, v76
	v_and_b32_e32 v211, 0xffff0000, v76
	v_lshlrev_b32_e32 v212, 16, v77
	v_and_b32_e32 v213, 0xffff0000, v77
	v_pk_fma_f32 v[210:211], v[22:23], v[206:207], v[210:211]
	v_pk_fma_f32 v[212:213], v[24:25], v[208:209], v[212:213]
	v_cvt_pk_bf16_f32 v76, v210, v211
	v_cvt_pk_bf16_f32 v77, v212, v213
	v_lshlrev_b32_e32 v206, 16, v110
	v_and_b32_e32 v207, 0xffff0000, v110
	v_lshlrev_b32_e32 v208, 16, v111
	v_and_b32_e32 v209, 0xffff0000, v111
	v_lshlrev_b32_e32 v210, 16, v78
	v_and_b32_e32 v211, 0xffff0000, v78
	v_lshlrev_b32_e32 v212, 16, v79
	v_and_b32_e32 v213, 0xffff0000, v79
	v_pk_fma_f32 v[210:211], v[26:27], v[206:207], v[210:211]
	v_pk_fma_f32 v[212:213], v[28:29], v[208:209], v[212:213]
	v_cvt_pk_bf16_f32 v78, v210, v211
	v_cvt_pk_bf16_f32 v79, v212, v213
	v_lshlrev_b32_e32 v206, 16, v112
	v_and_b32_e32 v207, 0xffff0000, v112
	v_lshlrev_b32_e32 v208, 16, v113
	v_and_b32_e32 v209, 0xffff0000, v113
	v_lshlrev_b32_e32 v210, 16, v80
	v_and_b32_e32 v211, 0xffff0000, v80
	v_lshlrev_b32_e32 v212, 16, v81
	v_and_b32_e32 v213, 0xffff0000, v81
	v_pk_fma_f32 v[210:211], v[30:31], v[206:207], v[210:211]
	v_pk_fma_f32 v[212:213], v[32:33], v[208:209], v[212:213]
	v_cvt_pk_bf16_f32 v80, v210, v211
	v_cvt_pk_bf16_f32 v81, v212, v213
	v_lshlrev_b32_e32 v206, 16, v114
	v_and_b32_e32 v207, 0xffff0000, v114
	v_lshlrev_b32_e32 v208, 16, v115
	v_and_b32_e32 v209, 0xffff0000, v115
	v_lshlrev_b32_e32 v210, 16, v82
	v_and_b32_e32 v211, 0xffff0000, v82
	v_lshlrev_b32_e32 v212, 16, v83
	v_and_b32_e32 v213, 0xffff0000, v83
	v_pk_fma_f32 v[210:211], v[34:35], v[206:207], v[210:211]
	v_pk_fma_f32 v[212:213], v[36:37], v[208:209], v[212:213]
	v_cvt_pk_bf16_f32 v82, v210, v211
	v_cvt_pk_bf16_f32 v83, v212, v213
	v_lshlrev_b32_e32 v206, 16, v116
	v_and_b32_e32 v207, 0xffff0000, v116
	v_lshlrev_b32_e32 v208, 16, v117
	v_and_b32_e32 v209, 0xffff0000, v117
	v_lshlrev_b32_e32 v210, 16, v84
	v_and_b32_e32 v211, 0xffff0000, v84
	v_lshlrev_b32_e32 v212, 16, v85
	v_and_b32_e32 v213, 0xffff0000, v85
; __device__ __forceinline__ void branch_phase(LAS unsigned char* lds, const bf16_t* __restrict__ O, const bf16_t* __restrict__ Wb, const bf16_t* __restrict__ Gt, bf16_t* __restrict__ MG, int tg, int wv) {
;     ...
;         BR_LOAD(0, 0);
;         asm volatile("s_waitcnt vmcnt(0)" ::: "memory"); __syncthreads();
;         for (int j = 0; j < 4; ++j) {
;             u32x2 gv[4][4];
;             f32x4 acc[4][4];
; #pragma unroll
;             for (int m = 0; m < 4; ++m)
; #pragma unroll
;                 for (int n = 0; n < 4; ++n) acc[m][n] = (f32x4){0.f, 0.f, 0.f, 0.f};
;             for (int kc = 0; kc < 4; ++kc) {
;                 const int c = j * 4 + kc;
;                 if (c + 1 < 16) BR_LOAD(c + 1, (c + 1) & 1);
;                 if (kc == 3) {
;                     const bf16_t* gp = Gt + (size_t)(rt * 128 + wm * 64 + fr) * ZC + j * 1024 + ct * 256 + wn * 64 + 4 * fq;
; #pragma unroll
;                     for (int m = 0; m < 4; ++m)
; #pragma unroll
;                         for (int n = 0; n < 4; ++n) gv[m][n] = *(const u32x2*)(gp + (size_t)m * 16 * ZC + n * 16);
;                 }
;                 LAS const unsigned char* st = lds + (c & 1) * STG;
; #pragma unroll
;                 for (int k = 0; k < 2; ++k) {
;                     __builtin_amdgcn_sched_barrier(0);
;                     bf16x8 af[4], bfr[4];
; #pragma unroll
;                     for (int m = 0; m < 4; ++m) af[m] = *(LAS const bf16x8*)(st + aoff + m * 2048 + k * 1024);
; #pragma unroll
;                     for (int n = 0; n < 4; ++n) bfr[n] = *(LAS const bf16x8*)(st + boff + n * 2048 + k * 1024);
; #pragma unroll
;                     for (int m = 0; m < 4; ++m)
; #pragma unroll
;                         for (int n = 0; n < 4; ++n) acc[m][n] = __builtin_amdgcn_mfma_f32_16x16x32_bf16(bfr[n], af[m], acc[m][n], 0, 0, 0);
;                 }
;                 asm volatile("s_waitcnt vmcnt(0)" ::: "memory"); __syncthreads();
;             }
; #pragma unroll
;             for (int m = 0; m < 4; ++m)
; #pragma unroll
;                 for (int n = 0; n < 4; ++n) { const u32x2 g = gv[m][n], sp = sum[m][n];
;                     const float s0_ = __builtin_bit_cast(float, sp.x << 16) + acc[m][n][0] * __builtin_bit_cast(float, g.x << 16), s1_ = __builtin_bit_cast(float, sp.x & 0xffff0000u) + acc[m][n][1] * __builtin_bit_cast(float, g.x & 0xffff0000u);
	v_pk_fma_f32 v[210:211], v[38:39], v[206:207], v[210:211]
	v_pk_fma_f32 v[212:213], v[40:41], v[208:209], v[212:213]
	v_cvt_pk_bf16_f32 v84, v210, v211
	v_cvt_pk_bf16_f32 v85, v212, v213
	v_lshlrev_b32_e32 v206, 16, v118
	v_and_b32_e32 v207, 0xffff0000, v118
	v_lshlrev_b32_e32 v208, 16, v119
	v_and_b32_e32 v209, 0xffff0000, v119
	v_lshlrev_b32_e32 v210, 16, v86
	v_and_b32_e32 v211, 0xffff0000, v86
	v_lshlrev_b32_e32 v212, 16, v87
	v_and_b32_e32 v213, 0xffff0000, v87
	v_pk_fma_f32 v[210:211], v[42:43], v[206:207], v[210:211]
	v_pk_fma_f32 v[212:213], v[44:45], v[208:209], v[212:213]
	v_cvt_pk_bf16_f32 v86, v210, v211
	v_cvt_pk_bf16_f32 v87, v212, v213
	v_lshlrev_b32_e32 v206, 16, v120
	v_and_b32_e32 v207, 0xffff0000, v120
	v_lshlrev_b32_e32 v208, 16, v121
	v_and_b32_e32 v209, 0xffff0000, v121
	v_lshlrev_b32_e32 v210, 16, v88
	v_and_b32_e32 v211, 0xffff0000, v88
	v_lshlrev_b32_e32 v212, 16, v89
	v_and_b32_e32 v213, 0xffff0000, v89
	v_pk_fma_f32 v[210:211], v[46:47], v[206:207], v[210:211]
	v_pk_fma_f32 v[212:213], v[48:49], v[208:209], v[212:213]
	v_cvt_pk_bf16_f32 v88, v210, v211
	v_cvt_pk_bf16_f32 v89, v212, v213
	v_lshlrev_b32_e32 v206, 16, v122
	v_and_b32_e32 v207, 0xffff0000, v122
	v_lshlrev_b32_e32 v208, 16, v123
	v_and_b32_e32 v209, 0xffff0000, v123
	v_lshlrev_b32_e32 v210, 16, v90
	v_and_b32_e32 v211, 0xffff0000, v90
	v_lshlrev_b32_e32 v212, 16, v91
	v_and_b32_e32 v213, 0xffff0000, v91
	v_pk_fma_f32 v[210:211], v[50:51], v[206:207], v[210:211]
	v_pk_fma_f32 v[212:213], v[52:53], v[208:209], v[212:213]
	v_cvt_pk_bf16_f32 v90, v210, v211
	v_cvt_pk_bf16_f32 v91, v212, v213
	v_lshlrev_b32_e32 v206, 16, v124
	v_and_b32_e32 v207, 0xffff0000, v124
	v_lshlrev_b32_e32 v208, 16, v125
	v_and_b32_e32 v209, 0xffff0000, v125
	v_lshlrev_b32_e32 v210, 16, v92
	v_and_b32_e32 v211, 0xffff0000, v92
	v_lshlrev_b32_e32 v212, 16, v93
	v_and_b32_e32 v213, 0xffff0000, v93
	v_pk_fma_f32 v[210:211], v[54:55], v[206:207], v[210:211]
	v_pk_fma_f32 v[212:213], v[56:57], v[208:209], v[212:213]
	v_cvt_pk_bf16_f32 v92, v210, v211
	v_cvt_pk_bf16_f32 v93, v212, v213
	v_lshlrev_b32_e32 v206, 16, v126
	v_and_b32_e32 v207, 0xffff0000, v126
	v_lshlrev_b32_e32 v208, 16, v127
	v_and_b32_e32 v209, 0xffff0000, v127
	v_lshlrev_b32_e32 v210, 16, v94
	v_and_b32_e32 v211, 0xffff0000, v94
	v_lshlrev_b32_e32 v212, 16, v95
	v_and_b32_e32 v213, 0xffff0000, v95
	v_pk_fma_f32 v[210:211], v[58:59], v[206:207], v[210:211]
	v_pk_fma_f32 v[212:213], v[60:61], v[208:209], v[212:213]
	v_cvt_pk_bf16_f32 v94, v210, v211
	v_cvt_pk_bf16_f32 v95, v212, v213
	v_lshlrev_b32_e32 v206, 16, v128
	v_and_b32_e32 v207, 0xffff0000, v128
	v_lshlrev_b32_e32 v208, 16, v129
	v_and_b32_e32 v209, 0xffff0000, v129
	v_lshlrev_b32_e32 v210, 16, v96
	v_and_b32_e32 v211, 0xffff0000, v96
	v_lshlrev_b32_e32 v212, 16, v97
	v_and_b32_e32 v213, 0xffff0000, v97
	v_pk_fma_f32 v[210:211], v[62:63], v[206:207], v[210:211]
	v_pk_fma_f32 v[212:213], v[64:65], v[208:209], v[212:213]
	v_cvt_pk_bf16_f32 v96, v210, v211
	v_cvt_pk_bf16_f32 v97, v212, v213
	s_add_u32 s66, s64, 0x500
	s_addc_u32 s67, s65, 0
	s_add_u32 s70, s68, 0x100100
	s_addc_u32 s71, s69, 0
	s_add_u32 s72, s70, 0x10000
	s_addc_u32 s73, s71, 0
	s_mov_b32 m0, s83
	s_nop 0
	global_load_lds_dwordx4 v197, s[66:67]
	s_add_i32 m0, s83, 0x2000
	s_nop 0
	global_load_lds_dwordx4 v198, s[66:67]
	s_add_i32 m0, s83, 0x4000
	s_nop 0
	global_load_lds_dwordx4 v199, s[70:71]
	s_add_i32 m0, s83, 0x6000
	s_nop 0
	global_load_lds_dwordx4 v200, s[70:71]
	s_mov_b32 m0, s60
	s_nop 0
	global_load_lds_dwordx4 v199, s[72:73]
	s_add_i32 m0, s60, 0x2000
	s_nop 0
	global_load_lds_dwordx4 v200, s[72:73]
	ds_read_b128 v[130:133], v216 offset:0
	ds_read_b128 v[134:137], v216 offset:2048
	ds_read_b128 v[138:141], v216 offset:4096
	ds_read_b128 v[142:145], v216 offset:6144
	ds_read_b128 v[162:165], v219 offset:0
	ds_read_b128 v[166:169], v219 offset:2048
	ds_read_b128 v[170:173], v219 offset:4096
	ds_read_b128 v[174:177], v219 offset:6144
	ds_read_b128 v[146:149], v216 offset:1024
	ds_read_b128 v[150:153], v216 offset:3072
	ds_read_b128 v[154:157], v216 offset:5120
	ds_read_b128 v[158:161], v216 offset:7168
	ds_read_b128 v[178:181], v219 offset:1024
	ds_read_b128 v[182:185], v219 offset:3072
	ds_read_b128 v[186:189], v219 offset:5120
	ds_read_b128 v[190:193], v219 offset:7168
	s_waitcnt lgkmcnt(8)
	v_mfma_f32_16x16x32_bf16 v[2:5], v[162:165], v[130:133], 0
	v_mfma_f32_16x16x32_bf16 v[6:9], v[166:169], v[130:133], 0
	v_mfma_f32_16x16x32_bf16 v[10:13], v[170:173], v[130:133], 0
	v_mfma_f32_16x16x32_bf16 v[14:17], v[174:177], v[130:133], 0
	v_mfma_f32_16x16x32_bf16 v[18:21], v[162:165], v[134:137], 0
	v_mfma_f32_16x16x32_bf16 v[22:25], v[166:169], v[134:137], 0
	v_mfma_f32_16x16x32_bf16 v[26:29], v[170:173], v[134:137], 0
	v_mfma_f32_16x16x32_bf16 v[30:33], v[174:177], v[134:137], 0
	v_mfma_f32_16x16x32_bf16 v[34:37], v[162:165], v[138:141], 0
	v_mfma_f32_16x16x32_bf16 v[38:41], v[166:169], v[138:141], 0
	v_mfma_f32_16x16x32_bf16 v[42:45], v[170:173], v[138:141], 0
	v_mfma_f32_16x16x32_bf16 v[46:49], v[174:177], v[138:141], 0
	v_mfma_f32_16x16x32_bf16 v[50:53], v[162:165], v[142:145], 0
	v_mfma_f32_16x16x32_bf16 v[54:57], v[166:169], v[142:145], 0
	v_mfma_f32_16x16x32_bf16 v[58:61], v[170:173], v[142:145], 0
	v_mfma_f32_16x16x32_bf16 v[62:65], v[174:177], v[142:145], 0
	s_waitcnt lgkmcnt(0)
	v_mfma_f32_16x16x32_bf16 v[2:5], v[178:181], v[146:149], v[2:5]
	v_mfma_f32_16x16x32_bf16 v[6:9], v[182:185], v[146:149], v[6:9]
	v_mfma_f32_16x16x32_bf16 v[10:13], v[186:189], v[146:149], v[10:13]
	v_mfma_f32_16x16x32_bf16 v[14:17], v[190:193], v[146:149], v[14:17]
	v_mfma_f32_16x16x32_bf16 v[18:21], v[178:181], v[150:153], v[18:21]
	v_mfma_f32_16x16x32_bf16 v[22:25], v[182:185], v[150:153], v[22:25]
	v_mfma_f32_16x16x32_bf16 v[26:29], v[186:189], v[150:153], v[26:29]
	v_mfma_f32_16x16x32_bf16 v[30:33], v[190:193], v[150:153], v[30:33]
	v_mfma_f32_16x16x32_bf16 v[34:37], v[178:181], v[154:157], v[34:37]
	v_mfma_f32_16x16x32_bf16 v[38:41], v[182:185], v[154:157], v[38:41]
	v_mfma_f32_16x16x32_bf16 v[42:45], v[186:189], v[154:157], v[42:45]
	v_mfma_f32_16x16x32_bf16 v[46:49], v[190:193], v[154:157], v[46:49]
	v_mfma_f32_16x16x32_bf16 v[50:53], v[178:181], v[158:161], v[50:53]
	v_mfma_f32_16x16x32_bf16 v[54:57], v[182:185], v[158:161], v[54:57]
	v_mfma_f32_16x16x32_bf16 v[58:61], v[186:189], v[158:161], v[58:61]
	v_mfma_f32_16x16x32_bf16 v[62:65], v[190:193], v[158:161], v[62:65]
	s_waitcnt vmcnt(6)
	s_barrier
; #define LAS __attribute__((address_space(3)))
; __device__ __forceinline__ void branch_phase(LAS unsigned char* lds, const bf16_t* __restrict__ O, const bf16_t* __restrict__ Wb, const bf16_t* __restrict__ Gt, bf16_t* __restrict__ MG, int tg, int wv) {
;     ...
;         BR_LOAD(0, 0);
;         asm volatile("s_waitcnt vmcnt(0)" ::: "memory"); __syncthreads();
;         for (int j = 0; j < 4; ++j) {
;             u32x2 gv[4][4];
;             f32x4 acc[4][4];
; #pragma unroll
;             for (int m = 0; m < 4; ++m)
; #pragma unroll
;                 for (int n = 0; n < 4; ++n) acc[m][n] = (f32x4){0.f, 0.f, 0.f, 0.f};
;             for (int kc = 0; kc < 4; ++kc) {
;                 const int c = j * 4 + kc;
;                 if (c + 1 < 16) BR_LOAD(c + 1, (c + 1) & 1);
;                 if (kc == 3) {
;                     const bf16_t* gp = Gt + (size_t)(rt * 128 + wm * 64 + fr) * ZC + j * 1024 + ct * 256 + wn * 64 + 4 * fq;
; #pragma unroll
;                     for (int m = 0; m < 4; ++m)
; #pragma unroll
;                         for (int n = 0; n < 4; ++n) gv[m][n] = *(const u32x2*)(gp + (size_t)m * 16 * ZC + n * 16);
;                 }
;                 LAS const unsigned char* st = lds + (c & 1) * STG;
; #pragma unroll
;                 for (int k = 0; k < 2; ++k) {
;                     __builtin_amdgcn_sched_barrier(0);
;                     bf16x8 af[4], bfr[4];
; #pragma unroll
;                     for (int m = 0; m < 4; ++m) af[m] = *(LAS const bf16x8*)(st + aoff + m * 2048 + k * 1024);
; #pragma unroll
;                     for (int n = 0; n < 4; ++n) bfr[n] = *(LAS const bf16x8*)(st + boff + n * 2048 + k * 1024);
; #pragma unroll
;                     for (int m = 0; m < 4; ++m)
; #pragma unroll
;                         for (int n = 0; n < 4; ++n) acc[m][n] = __builtin_amdgcn_mfma_f32_16x16x32_bf16(bfr[n], af[m], acc[m][n], 0, 0, 0);
;                 }
;                 asm volatile("s_waitcnt vmcnt(0)" ::: "memory"); __syncthreads();
	s_add_u32 s66, s64, 0x580
	s_addc_u32 s67, s65, 0
	s_add_u32 s70, s68, 0x100180
	s_addc_u32 s71, s69, 0
	s_add_u32 s72, s70, 0x10000
	s_addc_u32 s73, s71, 0
	s_mov_b32 m0, s84
	s_nop 0
	global_load_lds_dwordx4 v197, s[66:67]
	s_add_i32 m0, s84, 0x2000
	s_nop 0
	global_load_lds_dwordx4 v198, s[66:67]
	s_add_i32 m0, s84, 0x4000
	s_nop 0
	global_load_lds_dwordx4 v199, s[70:71]
	s_add_i32 m0, s84, 0x6000
	s_nop 0
	global_load_lds_dwordx4 v200, s[70:71]
	s_mov_b32 m0, s61
	s_nop 0
	global_load_lds_dwordx4 v199, s[72:73]
	s_add_i32 m0, s61, 0x2000
	s_nop 0
	global_load_lds_dwordx4 v200, s[72:73]
	s_add_u32 s80, s74, 0x1000
	s_addc_u32 s81, s75, 0
	global_load_dwordx4 v[98:101], v204, s[80:81] offset:0
	global_load_dwordx4 v[102:105], v204, s[80:81] offset:64
	s_add_u32 s80, s80, 0x20000
	s_addc_u32 s81, s81, 0
	global_load_dwordx4 v[106:109], v204, s[80:81] offset:0
	global_load_dwordx4 v[110:113], v204, s[80:81] offset:64
	s_add_u32 s80, s80, 0x20000
	s_addc_u32 s81, s81, 0
	global_load_dwordx4 v[114:117], v204, s[80:81] offset:0
	global_load_dwordx4 v[118:121], v204, s[80:81] offset:64
	s_add_u32 s80, s80, 0x20000
	s_addc_u32 s81, s81, 0
	global_load_dwordx4 v[122:125], v204, s[80:81] offset:0
	global_load_dwordx4 v[126:129], v204, s[80:81] offset:64
	ds_read_b128 v[130:133], v214 offset:0
	ds_read_b128 v[134:137], v214 offset:2048
	ds_read_b128 v[138:141], v214 offset:4096
	ds_read_b128 v[142:145], v214 offset:6144
	ds_read_b128 v[162:165], v217 offset:0
	ds_read_b128 v[166:169], v217 offset:2048
	ds_read_b128 v[170:173], v217 offset:4096
	ds_read_b128 v[174:177], v217 offset:6144
	ds_read_b128 v[146:149], v214 offset:1024
	ds_read_b128 v[150:153], v214 offset:3072
	ds_read_b128 v[154:157], v214 offset:5120
	ds_read_b128 v[158:161], v214 offset:7168
	ds_read_b128 v[178:181], v217 offset:1024
	ds_read_b128 v[182:185], v217 offset:3072
	ds_read_b128 v[186:189], v217 offset:5120
	ds_read_b128 v[190:193], v217 offset:7168
	s_waitcnt lgkmcnt(8)
	v_mfma_f32_16x16x32_bf16 v[2:5], v[162:165], v[130:133], v[2:5]
	v_mfma_f32_16x16x32_bf16 v[6:9], v[166:169], v[130:133], v[6:9]
	v_mfma_f32_16x16x32_bf16 v[10:13], v[170:173], v[130:133], v[10:13]
	v_mfma_f32_16x16x32_bf16 v[14:17], v[174:177], v[130:133], v[14:17]
	v_mfma_f32_16x16x32_bf16 v[18:21], v[162:165], v[134:137], v[18:21]
	v_mfma_f32_16x16x32_bf16 v[22:25], v[166:169], v[134:137], v[22:25]
	v_mfma_f32_16x16x32_bf16 v[26:29], v[170:173], v[134:137], v[26:29]
	v_mfma_f32_16x16x32_bf16 v[30:33], v[174:177], v[134:137], v[30:33]
	v_mfma_f32_16x16x32_bf16 v[34:37], v[162:165], v[138:141], v[34:37]
	v_mfma_f32_16x16x32_bf16 v[38:41], v[166:169], v[138:141], v[38:41]
	v_mfma_f32_16x16x32_bf16 v[42:45], v[170:173], v[138:141], v[42:45]
	v_mfma_f32_16x16x32_bf16 v[46:49], v[174:177], v[138:141], v[46:49]
	v_mfma_f32_16x16x32_bf16 v[50:53], v[162:165], v[142:145], v[50:53]
	v_mfma_f32_16x16x32_bf16 v[54:57], v[166:169], v[142:145], v[54:57]
	v_mfma_f32_16x16x32_bf16 v[58:61], v[170:173], v[142:145], v[58:61]
	v_mfma_f32_16x16x32_bf16 v[62:65], v[174:177], v[142:145], v[62:65]
	s_waitcnt lgkmcnt(0)
	v_mfma_f32_16x16x32_bf16 v[2:5], v[178:181], v[146:149], v[2:5]
	v_mfma_f32_16x16x32_bf16 v[6:9], v[182:185], v[146:149], v[6:9]
	v_mfma_f32_16x16x32_bf16 v[10:13], v[186:189], v[146:149], v[10:13]
	v_mfma_f32_16x16x32_bf16 v[14:17], v[190:193], v[146:149], v[14:17]
	v_mfma_f32_16x16x32_bf16 v[18:21], v[178:181], v[150:153], v[18:21]
	v_mfma_f32_16x16x32_bf16 v[22:25], v[182:185], v[150:153], v[22:25]
	v_mfma_f32_16x16x32_bf16 v[26:29], v[186:189], v[150:153], v[26:29]
	v_mfma_f32_16x16x32_bf16 v[30:33], v[190:193], v[150:153], v[30:33]
	v_mfma_f32_16x16x32_bf16 v[34:37], v[178:181], v[154:157], v[34:37]
	v_mfma_f32_16x16x32_bf16 v[38:41], v[182:185], v[154:157], v[38:41]
	v_mfma_f32_16x16x32_bf16 v[42:45], v[186:189], v[154:157], v[42:45]
	v_mfma_f32_16x16x32_bf16 v[46:49], v[190:193], v[154:157], v[46:49]
	v_mfma_f32_16x16x32_bf16 v[50:53], v[178:181], v[158:161], v[50:53]
	v_mfma_f32_16x16x32_bf16 v[54:57], v[182:185], v[158:161], v[54:57]
	v_mfma_f32_16x16x32_bf16 v[58:61], v[186:189], v[158:161], v[58:61]
	v_mfma_f32_16x16x32_bf16 v[62:65], v[190:193], v[158:161], v[62:65]
	s_waitcnt vmcnt(14)
	s_barrier
	s_add_u32 s66, s64, 0x600
	s_addc_u32 s67, s65, 0
	s_add_u32 s70, s68, 0x180000
	s_addc_u32 s71, s69, 0
	s_add_u32 s72, s70, 0x10000
	s_addc_u32 s73, s71, 0
	s_mov_b32 m0, s82
	s_nop 0
	global_load_lds_dwordx4 v197, s[66:67]
	s_add_i32 m0, s82, 0x2000
	s_nop 0
	global_load_lds_dwordx4 v198, s[66:67]
	s_add_i32 m0, s82, 0x4000
	s_nop 0
	global_load_lds_dwordx4 v199, s[70:71]
	s_add_i32 m0, s82, 0x6000
	s_nop 0
	global_load_lds_dwordx4 v200, s[70:71]
	s_mov_b32 m0, s85
	s_nop 0
	global_load_lds_dwordx4 v199, s[72:73]
	s_add_i32 m0, s85, 0x2000
	s_nop 0
	global_load_lds_dwordx4 v200, s[72:73]
	ds_read_b128 v[130:133], v215 offset:0
	ds_read_b128 v[134:137], v215 offset:2048
	ds_read_b128 v[138:141], v215 offset:4096
	ds_read_b128 v[142:145], v215 offset:6144
	ds_read_b128 v[162:165], v218 offset:0
	ds_read_b128 v[166:169], v218 offset:2048
	ds_read_b128 v[170:173], v218 offset:4096
	ds_read_b128 v[174:177], v218 offset:6144
	ds_read_b128 v[146:149], v215 offset:1024
	ds_read_b128 v[150:153], v215 offset:3072
	ds_read_b128 v[154:157], v215 offset:5120
	ds_read_b128 v[158:161], v215 offset:7168
	ds_read_b128 v[178:181], v218 offset:1024
	ds_read_b128 v[182:185], v218 offset:3072
	ds_read_b128 v[186:189], v218 offset:5120
	ds_read_b128 v[190:193], v218 offset:7168
	s_waitcnt lgkmcnt(8)
; #define LAS __attribute__((address_space(3)))
; __device__ __forceinline__ void branch_phase(LAS unsigned char* lds, const bf16_t* __restrict__ O, const bf16_t* __restrict__ Wb, const bf16_t* __restrict__ Gt, bf16_t* __restrict__ MG, int tg, int wv) {
;     ...
;             for (int kc = 0; kc < 4; ++kc) {
;                 const int c = j * 4 + kc;
;                 if (c + 1 < 16) BR_LOAD(c + 1, (c + 1) & 1);
;                 if (kc == 3) {
;                     const bf16_t* gp = Gt + (size_t)(rt * 128 + wm * 64 + fr) * ZC + j * 1024 + ct * 256 + wn * 64 + 4 * fq;
; #pragma unroll
;                     for (int m = 0; m < 4; ++m)
; #pragma unroll
;                         for (int n = 0; n < 4; ++n) gv[m][n] = *(const u32x2*)(gp + (size_t)m * 16 * ZC + n * 16);
;                 }
;                 LAS const unsigned char* st = lds + (c & 1) * STG;
; #pragma unroll
;                 for (int k = 0; k < 2; ++k) {
;                     __builtin_amdgcn_sched_barrier(0);
;                     bf16x8 af[4], bfr[4];
; #pragma unroll
;                     for (int m = 0; m < 4; ++m) af[m] = *(LAS const bf16x8*)(st + aoff + m * 2048 + k * 1024);
; #pragma unroll
;                     for (int n = 0; n < 4; ++n) bfr[n] = *(LAS const bf16x8*)(st + boff + n * 2048 + k * 1024);
; #pragma unroll
;                     for (int m = 0; m < 4; ++m)
; #pragma unroll
;                         for (int n = 0; n < 4; ++n) acc[m][n] = __builtin_amdgcn_mfma_f32_16x16x32_bf16(bfr[n], af[m], acc[m][n], 0, 0, 0);
;                 }
;                 asm volatile("s_waitcnt vmcnt(0)" ::: "memory"); __syncthreads();
	v_mfma_f32_16x16x32_bf16 v[2:5], v[162:165], v[130:133], v[2:5]
	v_mfma_f32_16x16x32_bf16 v[6:9], v[166:169], v[130:133], v[6:9]
	v_mfma_f32_16x16x32_bf16 v[10:13], v[170:173], v[130:133], v[10:13]
	v_mfma_f32_16x16x32_bf16 v[14:17], v[174:177], v[130:133], v[14:17]
	v_mfma_f32_16x16x32_bf16 v[18:21], v[162:165], v[134:137], v[18:21]
	v_mfma_f32_16x16x32_bf16 v[22:25], v[166:169], v[134:137], v[22:25]
	v_mfma_f32_16x16x32_bf16 v[26:29], v[170:173], v[134:137], v[26:29]
	v_mfma_f32_16x16x32_bf16 v[30:33], v[174:177], v[134:137], v[30:33]
	v_mfma_f32_16x16x32_bf16 v[34:37], v[162:165], v[138:141], v[34:37]
	v_mfma_f32_16x16x32_bf16 v[38:41], v[166:169], v[138:141], v[38:41]
	v_mfma_f32_16x16x32_bf16 v[42:45], v[170:173], v[138:141], v[42:45]
	v_mfma_f32_16x16x32_bf16 v[46:49], v[174:177], v[138:141], v[46:49]
	v_mfma_f32_16x16x32_bf16 v[50:53], v[162:165], v[142:145], v[50:53]
	v_mfma_f32_16x16x32_bf16 v[54:57], v[166:169], v[142:145], v[54:57]
	v_mfma_f32_16x16x32_bf16 v[58:61], v[170:173], v[142:145], v[58:61]
	v_mfma_f32_16x16x32_bf16 v[62:65], v[174:177], v[142:145], v[62:65]
	s_waitcnt lgkmcnt(0)
	v_mfma_f32_16x16x32_bf16 v[2:5], v[178:181], v[146:149], v[2:5]
	v_mfma_f32_16x16x32_bf16 v[6:9], v[182:185], v[146:149], v[6:9]
	v_mfma_f32_16x16x32_bf16 v[10:13], v[186:189], v[146:149], v[10:13]
	v_mfma_f32_16x16x32_bf16 v[14:17], v[190:193], v[146:149], v[14:17]
	v_mfma_f32_16x16x32_bf16 v[18:21], v[178:181], v[150:153], v[18:21]
	v_mfma_f32_16x16x32_bf16 v[22:25], v[182:185], v[150:153], v[22:25]
	v_mfma_f32_16x16x32_bf16 v[26:29], v[186:189], v[150:153], v[26:29]
	v_mfma_f32_16x16x32_bf16 v[30:33], v[190:193], v[150:153], v[30:33]
	v_mfma_f32_16x16x32_bf16 v[34:37], v[178:181], v[154:157], v[34:37]
	v_mfma_f32_16x16x32_bf16 v[38:41], v[182:185], v[154:157], v[38:41]
	v_mfma_f32_16x16x32_bf16 v[42:45], v[186:189], v[154:157], v[42:45]
	v_mfma_f32_16x16x32_bf16 v[46:49], v[190:193], v[154:157], v[46:49]
	v_mfma_f32_16x16x32_bf16 v[50:53], v[178:181], v[158:161], v[50:53]
	v_mfma_f32_16x16x32_bf16 v[54:57], v[182:185], v[158:161], v[54:57]
	v_mfma_f32_16x16x32_bf16 v[58:61], v[186:189], v[158:161], v[58:61]
	v_mfma_f32_16x16x32_bf16 v[62:65], v[190:193], v[158:161], v[62:65]
	s_waitcnt vmcnt(14)
	s_barrier
	s_add_u32 s66, s64, 0x680
	s_addc_u32 s67, s65, 0
	s_add_u32 s70, s68, 0x180080
	s_addc_u32 s71, s69, 0
	s_add_u32 s72, s70, 0x10000
	s_addc_u32 s73, s71, 0
	s_mov_b32 m0, s83
	s_nop 0
	global_load_lds_dwordx4 v197, s[66:67]
	s_add_i32 m0, s83, 0x2000
	s_nop 0
	global_load_lds_dwordx4 v198, s[66:67]
	s_add_i32 m0, s83, 0x4000
	s_nop 0
	global_load_lds_dwordx4 v199, s[70:71]
	s_add_i32 m0, s83, 0x6000
	s_nop 0
	global_load_lds_dwordx4 v200, s[70:71]
	s_mov_b32 m0, s60
	s_nop 0
	global_load_lds_dwordx4 v199, s[72:73]
	s_add_i32 m0, s60, 0x2000
	s_nop 0
	global_load_lds_dwordx4 v200, s[72:73]
	ds_read_b128 v[130:133], v216 offset:0
	ds_read_b128 v[134:137], v216 offset:2048
	ds_read_b128 v[138:141], v216 offset:4096
	ds_read_b128 v[142:145], v216 offset:6144
	ds_read_b128 v[162:165], v219 offset:0
	ds_read_b128 v[166:169], v219 offset:2048
	ds_read_b128 v[170:173], v219 offset:4096
	ds_read_b128 v[174:177], v219 offset:6144
	ds_read_b128 v[146:149], v216 offset:1024
	ds_read_b128 v[150:153], v216 offset:3072
	ds_read_b128 v[154:157], v216 offset:5120
	ds_read_b128 v[158:161], v216 offset:7168
	ds_read_b128 v[178:181], v219 offset:1024
	ds_read_b128 v[182:185], v219 offset:3072
	ds_read_b128 v[186:189], v219 offset:5120
	ds_read_b128 v[190:193], v219 offset:7168
	s_waitcnt lgkmcnt(8)
	v_mfma_f32_16x16x32_bf16 v[2:5], v[162:165], v[130:133], v[2:5]
	v_mfma_f32_16x16x32_bf16 v[6:9], v[166:169], v[130:133], v[6:9]
	v_mfma_f32_16x16x32_bf16 v[10:13], v[170:173], v[130:133], v[10:13]
	v_mfma_f32_16x16x32_bf16 v[14:17], v[174:177], v[130:133], v[14:17]
	v_mfma_f32_16x16x32_bf16 v[18:21], v[162:165], v[134:137], v[18:21]
	v_mfma_f32_16x16x32_bf16 v[22:25], v[166:169], v[134:137], v[22:25]
	v_mfma_f32_16x16x32_bf16 v[26:29], v[170:173], v[134:137], v[26:29]
	v_mfma_f32_16x16x32_bf16 v[30:33], v[174:177], v[134:137], v[30:33]
	v_mfma_f32_16x16x32_bf16 v[34:37], v[162:165], v[138:141], v[34:37]
	v_mfma_f32_16x16x32_bf16 v[38:41], v[166:169], v[138:141], v[38:41]
	v_mfma_f32_16x16x32_bf16 v[42:45], v[170:173], v[138:141], v[42:45]
	v_mfma_f32_16x16x32_bf16 v[46:49], v[174:177], v[138:141], v[46:49]
	v_mfma_f32_16x16x32_bf16 v[50:53], v[162:165], v[142:145], v[50:53]
	v_mfma_f32_16x16x32_bf16 v[54:57], v[166:169], v[142:145], v[54:57]
	v_mfma_f32_16x16x32_bf16 v[58:61], v[170:173], v[142:145], v[58:61]
	v_mfma_f32_16x16x32_bf16 v[62:65], v[174:177], v[142:145], v[62:65]
	s_waitcnt lgkmcnt(0)
	v_mfma_f32_16x16x32_bf16 v[2:5], v[178:181], v[146:149], v[2:5]
	v_mfma_f32_16x16x32_bf16 v[6:9], v[182:185], v[146:149], v[6:9]
	v_mfma_f32_16x16x32_bf16 v[10:13], v[186:189], v[146:149], v[10:13]
	v_mfma_f32_16x16x32_bf16 v[14:17], v[190:193], v[146:149], v[14:17]
	v_mfma_f32_16x16x32_bf16 v[18:21], v[178:181], v[150:153], v[18:21]
	v_mfma_f32_16x16x32_bf16 v[22:25], v[182:185], v[150:153], v[22:25]
	v_mfma_f32_16x16x32_bf16 v[26:29], v[186:189], v[150:153], v[26:29]
	v_mfma_f32_16x16x32_bf16 v[30:33], v[190:193], v[150:153], v[30:33]
	v_mfma_f32_16x16x32_bf16 v[34:37], v[178:181], v[154:157], v[34:37]
	v_mfma_f32_16x16x32_bf16 v[38:41], v[182:185], v[154:157], v[38:41]
	v_mfma_f32_16x16x32_bf16 v[42:45], v[186:189], v[154:157], v[42:45]
	v_mfma_f32_16x16x32_bf16 v[46:49], v[190:193], v[154:157], v[46:49]
	v_mfma_f32_16x16x32_bf16 v[50:53], v[178:181], v[158:161], v[50:53]
	v_mfma_f32_16x16x32_bf16 v[54:57], v[182:185], v[158:161], v[54:57]
	v_mfma_f32_16x16x32_bf16 v[58:61], v[186:189], v[158:161], v[58:61]
	v_mfma_f32_16x16x32_bf16 v[62:65], v[190:193], v[158:161], v[62:65]
	s_waitcnt vmcnt(6)
	s_barrier
; __device__ __forceinline__ unsigned cvtpk(float lo, float hi) { f32x2 v = {lo, hi}; bf16x2_t b = __builtin_convertvector(v, bf16x2_t); return __builtin_bit_cast(unsigned, b); }
; __device__ __forceinline__ void branch_phase(LAS unsigned char* lds, const bf16_t* __restrict__ O, const bf16_t* __restrict__ Wb, const bf16_t* __restrict__ Gt, bf16_t* __restrict__ MG, int tg, int wv) {
;     ...
; #pragma unroll
;             for (int m = 0; m < 4; ++m)
; #pragma unroll
;                 for (int n = 0; n < 4; ++n) { const u32x2 g = gv[m][n], sp = sum[m][n];
;                     const float s0_ = __builtin_bit_cast(float, sp.x << 16) + acc[m][n][0] * __builtin_bit_cast(float, g.x << 16), s1_ = __builtin_bit_cast(float, sp.x & 0xffff0000u) + acc[m][n][1] * __builtin_bit_cast(float, g.x & 0xffff0000u);
;                     const float s2_ = __builtin_bit_cast(float, sp.y << 16) + acc[m][n][2] * __builtin_bit_cast(float, g.y << 16), s3_ = __builtin_bit_cast(float, sp.y & 0xffff0000u) + acc[m][n][3] * __builtin_bit_cast(float, g.y & 0xffff0000u);
;                     sum[m][n] = (u32x2){cvtpk(s0_, s1_), cvtpk(s2_, s3_)}; }
	s_nop 7
	v_lshlrev_b32_e32 v206, 16, v98
	v_and_b32_e32 v207, 0xffff0000, v98
	v_lshlrev_b32_e32 v208, 16, v99
	v_and_b32_e32 v209, 0xffff0000, v99
	v_lshlrev_b32_e32 v210, 16, v66
	v_and_b32_e32 v211, 0xffff0000, v66
	v_lshlrev_b32_e32 v212, 16, v67
	v_and_b32_e32 v213, 0xffff0000, v67
	v_pk_fma_f32 v[210:211], v[2:3], v[206:207], v[210:211]
	v_pk_fma_f32 v[212:213], v[4:5], v[208:209], v[212:213]
	v_cvt_pk_bf16_f32 v66, v210, v211
	v_cvt_pk_bf16_f32 v67, v212, v213
	v_lshlrev_b32_e32 v206, 16, v100
	v_and_b32_e32 v207, 0xffff0000, v100
	v_lshlrev_b32_e32 v208, 16, v101
	v_and_b32_e32 v209, 0xffff0000, v101
	v_lshlrev_b32_e32 v210, 16, v68
	v_and_b32_e32 v211, 0xffff0000, v68
	v_lshlrev_b32_e32 v212, 16, v69
	v_and_b32_e32 v213, 0xffff0000, v69
	v_pk_fma_f32 v[210:211], v[6:7], v[206:207], v[210:211]
	v_pk_fma_f32 v[212:213], v[8:9], v[208:209], v[212:213]
	v_cvt_pk_bf16_f32 v68, v210, v211
	v_cvt_pk_bf16_f32 v69, v212, v213
	v_lshlrev_b32_e32 v206, 16, v102
	v_and_b32_e32 v207, 0xffff0000, v102
	v_lshlrev_b32_e32 v208, 16, v103
	v_and_b32_e32 v209, 0xffff0000, v103
	v_lshlrev_b32_e32 v210, 16, v70
	v_and_b32_e32 v211, 0xffff0000, v70
	v_lshlrev_b32_e32 v212, 16, v71
	v_and_b32_e32 v213, 0xffff0000, v71
	v_pk_fma_f32 v[210:211], v[10:11], v[206:207], v[210:211]
	v_pk_fma_f32 v[212:213], v[12:13], v[208:209], v[212:213]
	v_cvt_pk_bf16_f32 v70, v210, v211
	v_cvt_pk_bf16_f32 v71, v212, v213
	v_lshlrev_b32_e32 v206, 16, v104
	v_and_b32_e32 v207, 0xffff0000, v104
	v_lshlrev_b32_e32 v208, 16, v105
	v_and_b32_e32 v209, 0xffff0000, v105
	v_lshlrev_b32_e32 v210, 16, v72
	v_and_b32_e32 v211, 0xffff0000, v72
	v_lshlrev_b32_e32 v212, 16, v73
	v_and_b32_e32 v213, 0xffff0000, v73
	v_pk_fma_f32 v[210:211], v[14:15], v[206:207], v[210:211]
	v_pk_fma_f32 v[212:213], v[16:17], v[208:209], v[212:213]
	v_cvt_pk_bf16_f32 v72, v210, v211
	v_cvt_pk_bf16_f32 v73, v212, v213
	v_lshlrev_b32_e32 v206, 16, v106
	v_and_b32_e32 v207, 0xffff0000, v106
	v_lshlrev_b32_e32 v208, 16, v107
	v_and_b32_e32 v209, 0xffff0000, v107
	v_lshlrev_b32_e32 v210, 16, v74
	v_and_b32_e32 v211, 0xffff0000, v74
	v_lshlrev_b32_e32 v212, 16, v75
	v_and_b32_e32 v213, 0xffff0000, v75
	v_pk_fma_f32 v[210:211], v[18:19], v[206:207], v[210:211]
	v_pk_fma_f32 v[212:213], v[20:21], v[208:209], v[212:213]
	v_cvt_pk_bf16_f32 v74, v210, v211
	v_cvt_pk_bf16_f32 v75, v212, v213
	v_lshlrev_b32_e32 v206, 16, v108
	v_and_b32_e32 v207, 0xffff0000, v108
	v_lshlrev_b32_e32 v208, 16, v109
	v_and_b32_e32 v209, 0xffff0000, v109
	v_lshlrev_b32_e32 v210, 16, v76
	v_and_b32_e32 v211, 0xffff0000, v76
	v_lshlrev_b32_e32 v212, 16, v77
	v_and_b32_e32 v213, 0xffff0000, v77
	v_pk_fma_f32 v[210:211], v[22:23], v[206:207], v[210:211]
	v_pk_fma_f32 v[212:213], v[24:25], v[208:209], v[212:213]
	v_cvt_pk_bf16_f32 v76, v210, v211
	v_cvt_pk_bf16_f32 v77, v212, v213
	v_lshlrev_b32_e32 v206, 16, v110
	v_and_b32_e32 v207, 0xffff0000, v110
	v_lshlrev_b32_e32 v208, 16, v111
	v_and_b32_e32 v209, 0xffff0000, v111
	v_lshlrev_b32_e32 v210, 16, v78
	v_and_b32_e32 v211, 0xffff0000, v78
	v_lshlrev_b32_e32 v212, 16, v79
	v_and_b32_e32 v213, 0xffff0000, v79
	v_pk_fma_f32 v[210:211], v[26:27], v[206:207], v[210:211]
	v_pk_fma_f32 v[212:213], v[28:29], v[208:209], v[212:213]
	v_cvt_pk_bf16_f32 v78, v210, v211
	v_cvt_pk_bf16_f32 v79, v212, v213
	v_lshlrev_b32_e32 v206, 16, v112
	v_and_b32_e32 v207, 0xffff0000, v112
	v_lshlrev_b32_e32 v208, 16, v113
	v_and_b32_e32 v209, 0xffff0000, v113
	v_lshlrev_b32_e32 v210, 16, v80
	v_and_b32_e32 v211, 0xffff0000, v80
	v_lshlrev_b32_e32 v212, 16, v81
	v_and_b32_e32 v213, 0xffff0000, v81
	v_pk_fma_f32 v[210:211], v[30:31], v[206:207], v[210:211]
	v_pk_fma_f32 v[212:213], v[32:33], v[208:209], v[212:213]
	v_cvt_pk_bf16_f32 v80, v210, v211
	v_cvt_pk_bf16_f32 v81, v212, v213
	v_lshlrev_b32_e32 v206, 16, v114
	v_and_b32_e32 v207, 0xffff0000, v114
	v_lshlrev_b32_e32 v208, 16, v115
	v_and_b32_e32 v209, 0xffff0000, v115
	v_lshlrev_b32_e32 v210, 16, v82
	v_and_b32_e32 v211, 0xffff0000, v82
	v_lshlrev_b32_e32 v212, 16, v83
	v_and_b32_e32 v213, 0xffff0000, v83
	v_pk_fma_f32 v[210:211], v[34:35], v[206:207], v[210:211]
	v_pk_fma_f32 v[212:213], v[36:37], v[208:209], v[212:213]
	v_cvt_pk_bf16_f32 v82, v210, v211
	v_cvt_pk_bf16_f32 v83, v212, v213
	v_lshlrev_b32_e32 v206, 16, v116
	v_and_b32_e32 v207, 0xffff0000, v116
	v_lshlrev_b32_e32 v208, 16, v117
	v_and_b32_e32 v209, 0xffff0000, v117
	v_lshlrev_b32_e32 v210, 16, v84
	v_and_b32_e32 v211, 0xffff0000, v84
	v_lshlrev_b32_e32 v212, 16, v85
	v_and_b32_e32 v213, 0xffff0000, v85
	v_pk_fma_f32 v[210:211], v[38:39], v[206:207], v[210:211]
	v_pk_fma_f32 v[212:213], v[40:41], v[208:209], v[212:213]
	v_cvt_pk_bf16_f32 v84, v210, v211
	v_cvt_pk_bf16_f32 v85, v212, v213
	v_lshlrev_b32_e32 v206, 16, v118
	v_and_b32_e32 v207, 0xffff0000, v118
	v_lshlrev_b32_e32 v208, 16, v119
	v_and_b32_e32 v209, 0xffff0000, v119
	v_lshlrev_b32_e32 v210, 16, v86
	v_and_b32_e32 v211, 0xffff0000, v86
	v_lshlrev_b32_e32 v212, 16, v87
	v_and_b32_e32 v213, 0xffff0000, v87
	v_pk_fma_f32 v[210:211], v[42:43], v[206:207], v[210:211]
	v_pk_fma_f32 v[212:213], v[44:45], v[208:209], v[212:213]
	v_cvt_pk_bf16_f32 v86, v210, v211
	v_cvt_pk_bf16_f32 v87, v212, v213
	v_lshlrev_b32_e32 v206, 16, v120
	v_and_b32_e32 v207, 0xffff0000, v120
	v_lshlrev_b32_e32 v208, 16, v121
	v_and_b32_e32 v209, 0xffff0000, v121
	v_lshlrev_b32_e32 v210, 16, v88
	v_and_b32_e32 v211, 0xffff0000, v88
	v_lshlrev_b32_e32 v212, 16, v89
	v_and_b32_e32 v213, 0xffff0000, v89
	v_pk_fma_f32 v[210:211], v[46:47], v[206:207], v[210:211]
	v_pk_fma_f32 v[212:213], v[48:49], v[208:209], v[212:213]
	v_cvt_pk_bf16_f32 v88, v210, v211
; __device__ __forceinline__ void branch_phase(LAS unsigned char* lds, const bf16_t* __restrict__ O, const bf16_t* __restrict__ Wb, const bf16_t* __restrict__ Gt, bf16_t* __restrict__ MG, int tg, int wv) {
;     ...
;         BR_LOAD(0, 0);
;         asm volatile("s_waitcnt vmcnt(0)" ::: "memory"); __syncthreads();
;         for (int j = 0; j < 4; ++j) {
;             u32x2 gv[4][4];
;             f32x4 acc[4][4];
; #pragma unroll
;             for (int m = 0; m < 4; ++m)
; #pragma unroll
;                 for (int n = 0; n < 4; ++n) acc[m][n] = (f32x4){0.f, 0.f, 0.f, 0.f};
;             for (int kc = 0; kc < 4; ++kc) {
;                 const int c = j * 4 + kc;
;                 if (c + 1 < 16) BR_LOAD(c + 1, (c + 1) & 1);
;                 if (kc == 3) {
;                     const bf16_t* gp = Gt + (size_t)(rt * 128 + wm * 64 + fr) * ZC + j * 1024 + ct * 256 + wn * 64 + 4 * fq;
; #pragma unroll
;                     for (int m = 0; m < 4; ++m)
; #pragma unroll
;                         for (int n = 0; n < 4; ++n) gv[m][n] = *(const u32x2*)(gp + (size_t)m * 16 * ZC + n * 16);
;                 }
;                 LAS const unsigned char* st = lds + (c & 1) * STG;
; #pragma unroll
;                 for (int k = 0; k < 2; ++k) {
;                     __builtin_amdgcn_sched_barrier(0);
;                     bf16x8 af[4], bfr[4];
; #pragma unroll
;                     for (int m = 0; m < 4; ++m) af[m] = *(LAS const bf16x8*)(st + aoff + m * 2048 + k * 1024);
; #pragma unroll
;                     for (int n = 0; n < 4; ++n) bfr[n] = *(LAS const bf16x8*)(st + boff + n * 2048 + k * 1024);
; #pragma unroll
;                     for (int m = 0; m < 4; ++m)
; #pragma unroll
;                         for (int n = 0; n < 4; ++n) acc[m][n] = __builtin_amdgcn_mfma_f32_16x16x32_bf16(bfr[n], af[m], acc[m][n], 0, 0, 0);
;                 }
;                 asm volatile("s_waitcnt vmcnt(0)" ::: "memory"); __syncthreads();
;             }
; #pragma unroll
;             for (int m = 0; m < 4; ++m)
; #pragma unroll
;                 for (int n = 0; n < 4; ++n) { const u32x2 g = gv[m][n], sp = sum[m][n];
;                     const float s0_ = __builtin_bit_cast(float, sp.x << 16) + acc[m][n][0] * __builtin_bit_cast(float, g.x << 16), s1_ = __builtin_bit_cast(float, sp.x & 0xffff0000u) + acc[m][n][1] * __builtin_bit_cast(float, g.x & 0xffff0000u);
	v_cvt_pk_bf16_f32 v89, v212, v213
	v_lshlrev_b32_e32 v206, 16, v122
	v_and_b32_e32 v207, 0xffff0000, v122
	v_lshlrev_b32_e32 v208, 16, v123
	v_and_b32_e32 v209, 0xffff0000, v123
	v_lshlrev_b32_e32 v210, 16, v90
	v_and_b32_e32 v211, 0xffff0000, v90
	v_lshlrev_b32_e32 v212, 16, v91
	v_and_b32_e32 v213, 0xffff0000, v91
	v_pk_fma_f32 v[210:211], v[50:51], v[206:207], v[210:211]
	v_pk_fma_f32 v[212:213], v[52:53], v[208:209], v[212:213]
	v_cvt_pk_bf16_f32 v90, v210, v211
	v_cvt_pk_bf16_f32 v91, v212, v213
	v_lshlrev_b32_e32 v206, 16, v124
	v_and_b32_e32 v207, 0xffff0000, v124
	v_lshlrev_b32_e32 v208, 16, v125
	v_and_b32_e32 v209, 0xffff0000, v125
	v_lshlrev_b32_e32 v210, 16, v92
	v_and_b32_e32 v211, 0xffff0000, v92
	v_lshlrev_b32_e32 v212, 16, v93
	v_and_b32_e32 v213, 0xffff0000, v93
	v_pk_fma_f32 v[210:211], v[54:55], v[206:207], v[210:211]
	v_pk_fma_f32 v[212:213], v[56:57], v[208:209], v[212:213]
	v_cvt_pk_bf16_f32 v92, v210, v211
	v_cvt_pk_bf16_f32 v93, v212, v213
	v_lshlrev_b32_e32 v206, 16, v126
	v_and_b32_e32 v207, 0xffff0000, v126
	v_lshlrev_b32_e32 v208, 16, v127
	v_and_b32_e32 v209, 0xffff0000, v127
	v_lshlrev_b32_e32 v210, 16, v94
	v_and_b32_e32 v211, 0xffff0000, v94
	v_lshlrev_b32_e32 v212, 16, v95
	v_and_b32_e32 v213, 0xffff0000, v95
	v_pk_fma_f32 v[210:211], v[58:59], v[206:207], v[210:211]
	v_pk_fma_f32 v[212:213], v[60:61], v[208:209], v[212:213]
	v_cvt_pk_bf16_f32 v94, v210, v211
	v_cvt_pk_bf16_f32 v95, v212, v213
	v_lshlrev_b32_e32 v206, 16, v128
	v_and_b32_e32 v207, 0xffff0000, v128
	v_lshlrev_b32_e32 v208, 16, v129
	v_and_b32_e32 v209, 0xffff0000, v129
	v_lshlrev_b32_e32 v210, 16, v96
	v_and_b32_e32 v211, 0xffff0000, v96
	v_lshlrev_b32_e32 v212, 16, v97
	v_and_b32_e32 v213, 0xffff0000, v97
	v_pk_fma_f32 v[210:211], v[62:63], v[206:207], v[210:211]
	v_pk_fma_f32 v[212:213], v[64:65], v[208:209], v[212:213]
	v_cvt_pk_bf16_f32 v96, v210, v211
	v_cvt_pk_bf16_f32 v97, v212, v213
	s_add_u32 s66, s64, 0x700
	s_addc_u32 s67, s65, 0
	s_add_u32 s70, s68, 0x180100
	s_addc_u32 s71, s69, 0
	s_add_u32 s72, s70, 0x10000
	s_addc_u32 s73, s71, 0
	s_mov_b32 m0, s84
	s_nop 0
	global_load_lds_dwordx4 v197, s[66:67]
	s_add_i32 m0, s84, 0x2000
	s_nop 0
	global_load_lds_dwordx4 v198, s[66:67]
	s_add_i32 m0, s84, 0x4000
	s_nop 0
	global_load_lds_dwordx4 v199, s[70:71]
	s_add_i32 m0, s84, 0x6000
	s_nop 0
	global_load_lds_dwordx4 v200, s[70:71]
	s_mov_b32 m0, s61
	s_nop 0
	global_load_lds_dwordx4 v199, s[72:73]
	s_add_i32 m0, s61, 0x2000
	s_nop 0
	global_load_lds_dwordx4 v200, s[72:73]
	ds_read_b128 v[130:133], v214 offset:0
	ds_read_b128 v[134:137], v214 offset:2048
	ds_read_b128 v[138:141], v214 offset:4096
	ds_read_b128 v[142:145], v214 offset:6144
	ds_read_b128 v[162:165], v217 offset:0
	ds_read_b128 v[166:169], v217 offset:2048
	ds_read_b128 v[170:173], v217 offset:4096
	ds_read_b128 v[174:177], v217 offset:6144
	ds_read_b128 v[146:149], v214 offset:1024
	ds_read_b128 v[150:153], v214 offset:3072
	ds_read_b128 v[154:157], v214 offset:5120
	ds_read_b128 v[158:161], v214 offset:7168
	ds_read_b128 v[178:181], v217 offset:1024
	ds_read_b128 v[182:185], v217 offset:3072
	ds_read_b128 v[186:189], v217 offset:5120
	ds_read_b128 v[190:193], v217 offset:7168
	s_waitcnt lgkmcnt(8)
	v_mfma_f32_16x16x32_bf16 v[2:5], v[162:165], v[130:133], 0
	v_mfma_f32_16x16x32_bf16 v[6:9], v[166:169], v[130:133], 0
	v_mfma_f32_16x16x32_bf16 v[10:13], v[170:173], v[130:133], 0
	v_mfma_f32_16x16x32_bf16 v[14:17], v[174:177], v[130:133], 0
	v_mfma_f32_16x16x32_bf16 v[18:21], v[162:165], v[134:137], 0
	v_mfma_f32_16x16x32_bf16 v[22:25], v[166:169], v[134:137], 0
	v_mfma_f32_16x16x32_bf16 v[26:29], v[170:173], v[134:137], 0
	v_mfma_f32_16x16x32_bf16 v[30:33], v[174:177], v[134:137], 0
	v_mfma_f32_16x16x32_bf16 v[34:37], v[162:165], v[138:141], 0
	v_mfma_f32_16x16x32_bf16 v[38:41], v[166:169], v[138:141], 0
	v_mfma_f32_16x16x32_bf16 v[42:45], v[170:173], v[138:141], 0
	v_mfma_f32_16x16x32_bf16 v[46:49], v[174:177], v[138:141], 0
	v_mfma_f32_16x16x32_bf16 v[50:53], v[162:165], v[142:145], 0
	v_mfma_f32_16x16x32_bf16 v[54:57], v[166:169], v[142:145], 0
	v_mfma_f32_16x16x32_bf16 v[58:61], v[170:173], v[142:145], 0
	v_mfma_f32_16x16x32_bf16 v[62:65], v[174:177], v[142:145], 0
	s_waitcnt lgkmcnt(0)
	v_mfma_f32_16x16x32_bf16 v[2:5], v[178:181], v[146:149], v[2:5]
	v_mfma_f32_16x16x32_bf16 v[6:9], v[182:185], v[146:149], v[6:9]
	v_mfma_f32_16x16x32_bf16 v[10:13], v[186:189], v[146:149], v[10:13]
	v_mfma_f32_16x16x32_bf16 v[14:17], v[190:193], v[146:149], v[14:17]
	v_mfma_f32_16x16x32_bf16 v[18:21], v[178:181], v[150:153], v[18:21]
	v_mfma_f32_16x16x32_bf16 v[22:25], v[182:185], v[150:153], v[22:25]
	v_mfma_f32_16x16x32_bf16 v[26:29], v[186:189], v[150:153], v[26:29]
	v_mfma_f32_16x16x32_bf16 v[30:33], v[190:193], v[150:153], v[30:33]
	v_mfma_f32_16x16x32_bf16 v[34:37], v[178:181], v[154:157], v[34:37]
	v_mfma_f32_16x16x32_bf16 v[38:41], v[182:185], v[154:157], v[38:41]
	v_mfma_f32_16x16x32_bf16 v[42:45], v[186:189], v[154:157], v[42:45]
	v_mfma_f32_16x16x32_bf16 v[46:49], v[190:193], v[154:157], v[46:49]
	v_mfma_f32_16x16x32_bf16 v[50:53], v[178:181], v[158:161], v[50:53]
	v_mfma_f32_16x16x32_bf16 v[54:57], v[182:185], v[158:161], v[54:57]
	v_mfma_f32_16x16x32_bf16 v[58:61], v[186:189], v[158:161], v[58:61]
	v_mfma_f32_16x16x32_bf16 v[62:65], v[190:193], v[158:161], v[62:65]
	s_waitcnt vmcnt(6)
	s_barrier
; #define LAS __attribute__((address_space(3)))
; __device__ __forceinline__ void branch_phase(LAS unsigned char* lds, const bf16_t* __restrict__ O, const bf16_t* __restrict__ Wb, const bf16_t* __restrict__ Gt, bf16_t* __restrict__ MG, int tg, int wv) {
;     ...
;         BR_LOAD(0, 0);
;         asm volatile("s_waitcnt vmcnt(0)" ::: "memory"); __syncthreads();
;         for (int j = 0; j < 4; ++j) {
;             u32x2 gv[4][4];
;             f32x4 acc[4][4];
; #pragma unroll
;             for (int m = 0; m < 4; ++m)
; #pragma unroll
;                 for (int n = 0; n < 4; ++n) acc[m][n] = (f32x4){0.f, 0.f, 0.f, 0.f};
;             for (int kc = 0; kc < 4; ++kc) {
;                 const int c = j * 4 + kc;
;                 if (c + 1 < 16) BR_LOAD(c + 1, (c + 1) & 1);
;                 if (kc == 3) {
;                     const bf16_t* gp = Gt + (size_t)(rt * 128 + wm * 64 + fr) * ZC + j * 1024 + ct * 256 + wn * 64 + 4 * fq;
; #pragma unroll
;                     for (int m = 0; m < 4; ++m)
; #pragma unroll
;                         for (int n = 0; n < 4; ++n) gv[m][n] = *(const u32x2*)(gp + (size_t)m * 16 * ZC + n * 16);
;                 }
;                 LAS const unsigned char* st = lds + (c & 1) * STG;
; #pragma unroll
;                 for (int k = 0; k < 2; ++k) {
;                     __builtin_amdgcn_sched_barrier(0);
;                     bf16x8 af[4], bfr[4];
; #pragma unroll
;                     for (int m = 0; m < 4; ++m) af[m] = *(LAS const bf16x8*)(st + aoff + m * 2048 + k * 1024);
; #pragma unroll
;                     for (int n = 0; n < 4; ++n) bfr[n] = *(LAS const bf16x8*)(st + boff + n * 2048 + k * 1024);
; #pragma unroll
;                     for (int m = 0; m < 4; ++m)
; #pragma unroll
;                         for (int n = 0; n < 4; ++n) acc[m][n] = __builtin_amdgcn_mfma_f32_16x16x32_bf16(bfr[n], af[m], acc[m][n], 0, 0, 0);
;                 }
;                 asm volatile("s_waitcnt vmcnt(0)" ::: "memory"); __syncthreads();
	s_add_u32 s66, s64, 0x780
	s_addc_u32 s67, s65, 0
	s_add_u32 s70, s68, 0x180180
	s_addc_u32 s71, s69, 0
	s_add_u32 s72, s70, 0x10000
	s_addc_u32 s73, s71, 0
	s_mov_b32 m0, s82
	s_nop 0
	global_load_lds_dwordx4 v197, s[66:67]
	s_add_i32 m0, s82, 0x2000
	s_nop 0
	global_load_lds_dwordx4 v198, s[66:67]
	s_add_i32 m0, s82, 0x4000
	s_nop 0
	global_load_lds_dwordx4 v199, s[70:71]
	s_add_i32 m0, s82, 0x6000
	s_nop 0
	global_load_lds_dwordx4 v200, s[70:71]
	s_mov_b32 m0, s85
	s_nop 0
	global_load_lds_dwordx4 v199, s[72:73]
	s_add_i32 m0, s85, 0x2000
	s_nop 0
	global_load_lds_dwordx4 v200, s[72:73]
	s_add_u32 s80, s74, 0x1800
	s_addc_u32 s81, s75, 0
	global_load_dwordx4 v[98:101], v204, s[80:81] offset:0
	global_load_dwordx4 v[102:105], v204, s[80:81] offset:64
	s_add_u32 s80, s80, 0x20000
	s_addc_u32 s81, s81, 0
	global_load_dwordx4 v[106:109], v204, s[80:81] offset:0
	global_load_dwordx4 v[110:113], v204, s[80:81] offset:64
	s_add_u32 s80, s80, 0x20000
	s_addc_u32 s81, s81, 0
	global_load_dwordx4 v[114:117], v204, s[80:81] offset:0
	global_load_dwordx4 v[118:121], v204, s[80:81] offset:64
	s_add_u32 s80, s80, 0x20000
	s_addc_u32 s81, s81, 0
	global_load_dwordx4 v[122:125], v204, s[80:81] offset:0
	global_load_dwordx4 v[126:129], v204, s[80:81] offset:64
	ds_read_b128 v[130:133], v215 offset:0
	ds_read_b128 v[134:137], v215 offset:2048
	ds_read_b128 v[138:141], v215 offset:4096
	ds_read_b128 v[142:145], v215 offset:6144
	ds_read_b128 v[162:165], v218 offset:0
	ds_read_b128 v[166:169], v218 offset:2048
	ds_read_b128 v[170:173], v218 offset:4096
	ds_read_b128 v[174:177], v218 offset:6144
	ds_read_b128 v[146:149], v215 offset:1024
	ds_read_b128 v[150:153], v215 offset:3072
	ds_read_b128 v[154:157], v215 offset:5120
	ds_read_b128 v[158:161], v215 offset:7168
	ds_read_b128 v[178:181], v218 offset:1024
	ds_read_b128 v[182:185], v218 offset:3072
	ds_read_b128 v[186:189], v218 offset:5120
	ds_read_b128 v[190:193], v218 offset:7168
	s_waitcnt lgkmcnt(8)
	v_mfma_f32_16x16x32_bf16 v[2:5], v[162:165], v[130:133], v[2:5]
	v_mfma_f32_16x16x32_bf16 v[6:9], v[166:169], v[130:133], v[6:9]
	v_mfma_f32_16x16x32_bf16 v[10:13], v[170:173], v[130:133], v[10:13]
	v_mfma_f32_16x16x32_bf16 v[14:17], v[174:177], v[130:133], v[14:17]
	v_mfma_f32_16x16x32_bf16 v[18:21], v[162:165], v[134:137], v[18:21]
	v_mfma_f32_16x16x32_bf16 v[22:25], v[166:169], v[134:137], v[22:25]
	v_mfma_f32_16x16x32_bf16 v[26:29], v[170:173], v[134:137], v[26:29]
	v_mfma_f32_16x16x32_bf16 v[30:33], v[174:177], v[134:137], v[30:33]
	v_mfma_f32_16x16x32_bf16 v[34:37], v[162:165], v[138:141], v[34:37]
	v_mfma_f32_16x16x32_bf16 v[38:41], v[166:169], v[138:141], v[38:41]
	v_mfma_f32_16x16x32_bf16 v[42:45], v[170:173], v[138:141], v[42:45]
	v_mfma_f32_16x16x32_bf16 v[46:49], v[174:177], v[138:141], v[46:49]
	v_mfma_f32_16x16x32_bf16 v[50:53], v[162:165], v[142:145], v[50:53]
	v_mfma_f32_16x16x32_bf16 v[54:57], v[166:169], v[142:145], v[54:57]
	v_mfma_f32_16x16x32_bf16 v[58:61], v[170:173], v[142:145], v[58:61]
	v_mfma_f32_16x16x32_bf16 v[62:65], v[174:177], v[142:145], v[62:65]
	s_waitcnt lgkmcnt(0)
	v_mfma_f32_16x16x32_bf16 v[2:5], v[178:181], v[146:149], v[2:5]
	v_mfma_f32_16x16x32_bf16 v[6:9], v[182:185], v[146:149], v[6:9]
	v_mfma_f32_16x16x32_bf16 v[10:13], v[186:189], v[146:149], v[10:13]
	v_mfma_f32_16x16x32_bf16 v[14:17], v[190:193], v[146:149], v[14:17]
	v_mfma_f32_16x16x32_bf16 v[18:21], v[178:181], v[150:153], v[18:21]
	v_mfma_f32_16x16x32_bf16 v[22:25], v[182:185], v[150:153], v[22:25]
	v_mfma_f32_16x16x32_bf16 v[26:29], v[186:189], v[150:153], v[26:29]
	v_mfma_f32_16x16x32_bf16 v[30:33], v[190:193], v[150:153], v[30:33]
	v_mfma_f32_16x16x32_bf16 v[34:37], v[178:181], v[154:157], v[34:37]
	v_mfma_f32_16x16x32_bf16 v[38:41], v[182:185], v[154:157], v[38:41]
	v_mfma_f32_16x16x32_bf16 v[42:45], v[186:189], v[154:157], v[42:45]
	v_mfma_f32_16x16x32_bf16 v[46:49], v[190:193], v[154:157], v[46:49]
	v_mfma_f32_16x16x32_bf16 v[50:53], v[178:181], v[158:161], v[50:53]
	v_mfma_f32_16x16x32_bf16 v[54:57], v[182:185], v[158:161], v[54:57]
	v_mfma_f32_16x16x32_bf16 v[58:61], v[186:189], v[158:161], v[58:61]
	v_mfma_f32_16x16x32_bf16 v[62:65], v[190:193], v[158:161], v[62:65]
	s_waitcnt vmcnt(14)
	s_barrier
	ds_read_b128 v[130:133], v216 offset:0
	ds_read_b128 v[134:137], v216 offset:2048
	ds_read_b128 v[138:141], v216 offset:4096
	ds_read_b128 v[142:145], v216 offset:6144
	ds_read_b128 v[162:165], v219 offset:0
	ds_read_b128 v[166:169], v219 offset:2048
	ds_read_b128 v[170:173], v219 offset:4096
	ds_read_b128 v[174:177], v219 offset:6144
	ds_read_b128 v[146:149], v216 offset:1024
	ds_read_b128 v[150:153], v216 offset:3072
	ds_read_b128 v[154:157], v216 offset:5120
	ds_read_b128 v[158:161], v216 offset:7168
	ds_read_b128 v[178:181], v219 offset:1024
	ds_read_b128 v[182:185], v219 offset:3072
	ds_read_b128 v[186:189], v219 offset:5120
	ds_read_b128 v[190:193], v219 offset:7168
	s_waitcnt lgkmcnt(8)
	v_mfma_f32_16x16x32_bf16 v[2:5], v[162:165], v[130:133], v[2:5]
	v_mfma_f32_16x16x32_bf16 v[6:9], v[166:169], v[130:133], v[6:9]
	v_mfma_f32_16x16x32_bf16 v[10:13], v[170:173], v[130:133], v[10:13]
	v_mfma_f32_16x16x32_bf16 v[14:17], v[174:177], v[130:133], v[14:17]
	v_mfma_f32_16x16x32_bf16 v[18:21], v[162:165], v[134:137], v[18:21]
	v_mfma_f32_16x16x32_bf16 v[22:25], v[166:169], v[134:137], v[22:25]
	v_mfma_f32_16x16x32_bf16 v[26:29], v[170:173], v[134:137], v[26:29]
	v_mfma_f32_16x16x32_bf16 v[30:33], v[174:177], v[134:137], v[30:33]
	v_mfma_f32_16x16x32_bf16 v[34:37], v[162:165], v[138:141], v[34:37]
	v_mfma_f32_16x16x32_bf16 v[38:41], v[166:169], v[138:141], v[38:41]
	v_mfma_f32_16x16x32_bf16 v[42:45], v[170:173], v[138:141], v[42:45]
	v_mfma_f32_16x16x32_bf16 v[46:49], v[174:177], v[138:141], v[46:49]
	v_mfma_f32_16x16x32_bf16 v[50:53], v[162:165], v[142:145], v[50:53]
	v_mfma_f32_16x16x32_bf16 v[54:57], v[166:169], v[142:145], v[54:57]
	v_mfma_f32_16x16x32_bf16 v[58:61], v[170:173], v[142:145], v[58:61]
	v_mfma_f32_16x16x32_bf16 v[62:65], v[174:177], v[142:145], v[62:65]
	s_waitcnt lgkmcnt(0)
; #define LAS __attribute__((address_space(3)))
; __device__ __forceinline__ void branch_phase(LAS unsigned char* lds, const bf16_t* __restrict__ O, const bf16_t* __restrict__ Wb, const bf16_t* __restrict__ Gt, bf16_t* __restrict__ MG, int tg, int wv) {
;     ...
;     for (int tile = vb; tile < ntile; tile += G_) {
;         const int rt = tile >> 2, ct = tile & 3;
;         const bf16_t* Ab = O + (size_t)(rt * 128) * 1024;
;         u32x2 sum[4][4];
; #pragma unroll
;         for (int m = 0; m < 4; ++m)
; #pragma unroll
;             for (int n = 0; n < 4; ++n) sum[m][n] = (u32x2){0u, 0u};
;     ...
;         BR_LOAD(0, 0);
;         asm volatile("s_waitcnt vmcnt(0)" ::: "memory"); __syncthreads();
;         for (int j = 0; j < 4; ++j) {
;             u32x2 gv[4][4];
;             f32x4 acc[4][4];
; #pragma unroll
;             for (int m = 0; m < 4; ++m)
; #pragma unroll
;                 for (int n = 0; n < 4; ++n) acc[m][n] = (f32x4){0.f, 0.f, 0.f, 0.f};
;             for (int kc = 0; kc < 4; ++kc) {
;                 const int c = j * 4 + kc;
;                 if (c + 1 < 16) BR_LOAD(c + 1, (c + 1) & 1);
;                 if (kc == 3) {
;                     const bf16_t* gp = Gt + (size_t)(rt * 128 + wm * 64 + fr) * ZC + j * 1024 + ct * 256 + wn * 64 + 4 * fq;
; #pragma unroll
;                     for (int m = 0; m < 4; ++m)
; #pragma unroll
;                         for (int n = 0; n < 4; ++n) gv[m][n] = *(const u32x2*)(gp + (size_t)m * 16 * ZC + n * 16);
;                 }
;                 LAS const unsigned char* st = lds + (c & 1) * STG;
; #pragma unroll
;                 for (int k = 0; k < 2; ++k) {
;                     __builtin_amdgcn_sched_barrier(0);
;                     bf16x8 af[4], bfr[4];
; #pragma unroll
;                     for (int m = 0; m < 4; ++m) af[m] = *(LAS const bf16x8*)(st + aoff + m * 2048 + k * 1024);
; #pragma unroll
;                     for (int n = 0; n < 4; ++n) bfr[n] = *(LAS const bf16x8*)(st + boff + n * 2048 + k * 1024);
; #pragma unroll
;                     for (int m = 0; m < 4; ++m)
; #pragma unroll
;                         for (int n = 0; n < 4; ++n) acc[m][n] = __builtin_amdgcn_mfma_f32_16x16x32_bf16(bfr[n], af[m], acc[m][n], 0, 0, 0);
;                 }
;                 asm volatile("s_waitcnt vmcnt(0)" ::: "memory"); __syncthreads();
	v_mfma_f32_16x16x32_bf16 v[2:5], v[178:181], v[146:149], v[2:5]
	v_mfma_f32_16x16x32_bf16 v[6:9], v[182:185], v[146:149], v[6:9]
	v_mfma_f32_16x16x32_bf16 v[10:13], v[186:189], v[146:149], v[10:13]
	v_mfma_f32_16x16x32_bf16 v[14:17], v[190:193], v[146:149], v[14:17]
	v_mfma_f32_16x16x32_bf16 v[18:21], v[178:181], v[150:153], v[18:21]
	v_mfma_f32_16x16x32_bf16 v[22:25], v[182:185], v[150:153], v[22:25]
	v_mfma_f32_16x16x32_bf16 v[26:29], v[186:189], v[150:153], v[26:29]
	v_mfma_f32_16x16x32_bf16 v[30:33], v[190:193], v[150:153], v[30:33]
	v_mfma_f32_16x16x32_bf16 v[34:37], v[178:181], v[154:157], v[34:37]
	v_mfma_f32_16x16x32_bf16 v[38:41], v[182:185], v[154:157], v[38:41]
	v_mfma_f32_16x16x32_bf16 v[42:45], v[186:189], v[154:157], v[42:45]
	v_mfma_f32_16x16x32_bf16 v[46:49], v[190:193], v[154:157], v[46:49]
	v_mfma_f32_16x16x32_bf16 v[50:53], v[178:181], v[158:161], v[50:53]
	v_mfma_f32_16x16x32_bf16 v[54:57], v[182:185], v[158:161], v[54:57]
	v_mfma_f32_16x16x32_bf16 v[58:61], v[186:189], v[158:161], v[58:61]
	v_mfma_f32_16x16x32_bf16 v[62:65], v[190:193], v[158:161], v[62:65]
	s_waitcnt vmcnt(0)
	s_barrier
	s_add_i32 s79, s5, s4
	s_cmp_lt_i32 s79, s6
	s_cbranch_scc0 .Lph6_nopf
	s_add_u32 s64, s64, s62
	s_addc_u32 s65, s65, 0
	s_add_u32 s66, s64, 0x0
	s_addc_u32 s67, s65, 0
	s_add_u32 s70, s68, 0x0
	s_addc_u32 s71, s69, 0
	s_add_u32 s72, s70, 0x10000
	s_addc_u32 s73, s71, 0
	s_mov_b32 m0, s83
	s_nop 0
	global_load_lds_dwordx4 v197, s[66:67]
	s_add_i32 m0, s83, 0x2000
	s_nop 0
	global_load_lds_dwordx4 v198, s[66:67]
	s_add_i32 m0, s83, 0x4000
	s_nop 0
	global_load_lds_dwordx4 v199, s[70:71]
	s_add_i32 m0, s83, 0x6000
	s_nop 0
	global_load_lds_dwordx4 v200, s[70:71]
	s_mov_b32 m0, s60
	s_nop 0
	global_load_lds_dwordx4 v199, s[72:73]
	s_add_i32 m0, s60, 0x2000
	s_nop 0
	global_load_lds_dwordx4 v200, s[72:73]
	s_add_u32 s66, s64, 0x80
	s_addc_u32 s67, s65, 0
	s_add_u32 s70, s68, 0x80
	s_addc_u32 s71, s69, 0
	s_add_u32 s72, s70, 0x10000
	s_addc_u32 s73, s71, 0
	s_mov_b32 m0, s84
	s_nop 0
	global_load_lds_dwordx4 v197, s[66:67]
	s_add_i32 m0, s84, 0x2000
	s_nop 0
	global_load_lds_dwordx4 v198, s[66:67]
	s_add_i32 m0, s84, 0x4000
	s_nop 0
	global_load_lds_dwordx4 v199, s[70:71]
	s_add_i32 m0, s84, 0x6000
	s_nop 0
	global_load_lds_dwordx4 v200, s[70:71]
	s_mov_b32 m0, s61
	s_nop 0
	global_load_lds_dwordx4 v199, s[72:73]
	s_add_i32 m0, s61, 0x2000
	s_nop 0
	global_load_lds_dwordx4 v200, s[72:73]
.Lph6_nopf:
	ds_read_b128 v[130:133], v214 offset:0
	ds_read_b128 v[134:137], v214 offset:2048
	ds_read_b128 v[138:141], v214 offset:4096
	ds_read_b128 v[142:145], v214 offset:6144
	ds_read_b128 v[162:165], v217 offset:0
	ds_read_b128 v[166:169], v217 offset:2048
	ds_read_b128 v[170:173], v217 offset:4096
	ds_read_b128 v[174:177], v217 offset:6144
	ds_read_b128 v[146:149], v214 offset:1024
	ds_read_b128 v[150:153], v214 offset:3072
	ds_read_b128 v[154:157], v214 offset:5120
	ds_read_b128 v[158:161], v214 offset:7168
	ds_read_b128 v[178:181], v217 offset:1024
	ds_read_b128 v[182:185], v217 offset:3072
	ds_read_b128 v[186:189], v217 offset:5120
	ds_read_b128 v[190:193], v217 offset:7168
	s_waitcnt lgkmcnt(8)
	v_mfma_f32_16x16x32_bf16 v[2:5], v[162:165], v[130:133], v[2:5]
	v_mfma_f32_16x16x32_bf16 v[6:9], v[166:169], v[130:133], v[6:9]
	v_mfma_f32_16x16x32_bf16 v[10:13], v[170:173], v[130:133], v[10:13]
	v_mfma_f32_16x16x32_bf16 v[14:17], v[174:177], v[130:133], v[14:17]
	v_mfma_f32_16x16x32_bf16 v[18:21], v[162:165], v[134:137], v[18:21]
	v_mfma_f32_16x16x32_bf16 v[22:25], v[166:169], v[134:137], v[22:25]
	v_mfma_f32_16x16x32_bf16 v[26:29], v[170:173], v[134:137], v[26:29]
	v_mfma_f32_16x16x32_bf16 v[30:33], v[174:177], v[134:137], v[30:33]
	v_mfma_f32_16x16x32_bf16 v[34:37], v[162:165], v[138:141], v[34:37]
	v_mfma_f32_16x16x32_bf16 v[38:41], v[166:169], v[138:141], v[38:41]
	v_mfma_f32_16x16x32_bf16 v[42:45], v[170:173], v[138:141], v[42:45]
	v_mfma_f32_16x16x32_bf16 v[46:49], v[174:177], v[138:141], v[46:49]
	v_mfma_f32_16x16x32_bf16 v[50:53], v[162:165], v[142:145], v[50:53]
	v_mfma_f32_16x16x32_bf16 v[54:57], v[166:169], v[142:145], v[54:57]
	v_mfma_f32_16x16x32_bf16 v[58:61], v[170:173], v[142:145], v[58:61]
	v_mfma_f32_16x16x32_bf16 v[62:65], v[174:177], v[142:145], v[62:65]
	s_waitcnt lgkmcnt(0)
; __device__ __forceinline__ unsigned cvtpk(float lo, float hi) { f32x2 v = {lo, hi}; bf16x2_t b = __builtin_convertvector(v, bf16x2_t); return __builtin_bit_cast(unsigned, b); }
; __device__ __forceinline__ void branch_phase(LAS unsigned char* lds, const bf16_t* __restrict__ O, const bf16_t* __restrict__ Wb, const bf16_t* __restrict__ Gt, bf16_t* __restrict__ MG, int tg, int wv) {
;     ...
;                     for (int m = 0; m < 4; ++m)
; #pragma unroll
;                         for (int n = 0; n < 4; ++n) acc[m][n] = __builtin_amdgcn_mfma_f32_16x16x32_bf16(bfr[n], af[m], acc[m][n], 0, 0, 0);
;                 }
;                 asm volatile("s_waitcnt vmcnt(0)" ::: "memory"); __syncthreads();
;             }
; #pragma unroll
;             for (int m = 0; m < 4; ++m)
; #pragma unroll
;                 for (int n = 0; n < 4; ++n) { const u32x2 g = gv[m][n], sp = sum[m][n];
;                     const float s0_ = __builtin_bit_cast(float, sp.x << 16) + acc[m][n][0] * __builtin_bit_cast(float, g.x << 16), s1_ = __builtin_bit_cast(float, sp.x & 0xffff0000u) + acc[m][n][1] * __builtin_bit_cast(float, g.x & 0xffff0000u);
;                     const float s2_ = __builtin_bit_cast(float, sp.y << 16) + acc[m][n][2] * __builtin_bit_cast(float, g.y << 16), s3_ = __builtin_bit_cast(float, sp.y & 0xffff0000u) + acc[m][n][3] * __builtin_bit_cast(float, g.y & 0xffff0000u);
;                     sum[m][n] = (u32x2){cvtpk(s0_, s1_), cvtpk(s2_, s3_)}; }
	v_mfma_f32_16x16x32_bf16 v[2:5], v[178:181], v[146:149], v[2:5]
	v_mfma_f32_16x16x32_bf16 v[6:9], v[182:185], v[146:149], v[6:9]
	v_mfma_f32_16x16x32_bf16 v[10:13], v[186:189], v[146:149], v[10:13]
	v_mfma_f32_16x16x32_bf16 v[14:17], v[190:193], v[146:149], v[14:17]
	v_mfma_f32_16x16x32_bf16 v[18:21], v[178:181], v[150:153], v[18:21]
	v_mfma_f32_16x16x32_bf16 v[22:25], v[182:185], v[150:153], v[22:25]
	v_mfma_f32_16x16x32_bf16 v[26:29], v[186:189], v[150:153], v[26:29]
	v_mfma_f32_16x16x32_bf16 v[30:33], v[190:193], v[150:153], v[30:33]
	v_mfma_f32_16x16x32_bf16 v[34:37], v[178:181], v[154:157], v[34:37]
	v_mfma_f32_16x16x32_bf16 v[38:41], v[182:185], v[154:157], v[38:41]
	v_mfma_f32_16x16x32_bf16 v[42:45], v[186:189], v[154:157], v[42:45]
	v_mfma_f32_16x16x32_bf16 v[46:49], v[190:193], v[154:157], v[46:49]
	v_mfma_f32_16x16x32_bf16 v[50:53], v[178:181], v[158:161], v[50:53]
	v_mfma_f32_16x16x32_bf16 v[54:57], v[182:185], v[158:161], v[54:57]
	v_mfma_f32_16x16x32_bf16 v[58:61], v[186:189], v[158:161], v[58:61]
	v_mfma_f32_16x16x32_bf16 v[62:65], v[190:193], v[158:161], v[62:65]
	s_nop 7
	v_lshlrev_b32_e32 v206, 16, v98
	v_and_b32_e32 v207, 0xffff0000, v98
	v_lshlrev_b32_e32 v208, 16, v99
	v_and_b32_e32 v209, 0xffff0000, v99
	v_lshlrev_b32_e32 v210, 16, v66
	v_and_b32_e32 v211, 0xffff0000, v66
	v_lshlrev_b32_e32 v212, 16, v67
	v_and_b32_e32 v213, 0xffff0000, v67
	v_pk_fma_f32 v[210:211], v[2:3], v[206:207], v[210:211]
	v_pk_fma_f32 v[212:213], v[4:5], v[208:209], v[212:213]
	v_cvt_pk_bf16_f32 v66, v210, v211
	v_cvt_pk_bf16_f32 v67, v212, v213
	v_lshlrev_b32_e32 v206, 16, v100
	v_and_b32_e32 v207, 0xffff0000, v100
	v_lshlrev_b32_e32 v208, 16, v101
	v_and_b32_e32 v209, 0xffff0000, v101
	v_lshlrev_b32_e32 v210, 16, v68
	v_and_b32_e32 v211, 0xffff0000, v68
	v_lshlrev_b32_e32 v212, 16, v69
	v_and_b32_e32 v213, 0xffff0000, v69
	v_pk_fma_f32 v[210:211], v[6:7], v[206:207], v[210:211]
	v_pk_fma_f32 v[212:213], v[8:9], v[208:209], v[212:213]
	v_cvt_pk_bf16_f32 v68, v210, v211
	v_cvt_pk_bf16_f32 v69, v212, v213
	v_lshlrev_b32_e32 v206, 16, v102
	v_and_b32_e32 v207, 0xffff0000, v102
	v_lshlrev_b32_e32 v208, 16, v103
	v_and_b32_e32 v209, 0xffff0000, v103
	v_lshlrev_b32_e32 v210, 16, v70
	v_and_b32_e32 v211, 0xffff0000, v70
	v_lshlrev_b32_e32 v212, 16, v71
	v_and_b32_e32 v213, 0xffff0000, v71
	v_pk_fma_f32 v[210:211], v[10:11], v[206:207], v[210:211]
	v_pk_fma_f32 v[212:213], v[12:13], v[208:209], v[212:213]
	v_cvt_pk_bf16_f32 v70, v210, v211
	v_cvt_pk_bf16_f32 v71, v212, v213
	v_lshlrev_b32_e32 v206, 16, v104
	v_and_b32_e32 v207, 0xffff0000, v104
	v_lshlrev_b32_e32 v208, 16, v105
	v_and_b32_e32 v209, 0xffff0000, v105
	v_lshlrev_b32_e32 v210, 16, v72
	v_and_b32_e32 v211, 0xffff0000, v72
	v_lshlrev_b32_e32 v212, 16, v73
	v_and_b32_e32 v213, 0xffff0000, v73
	v_pk_fma_f32 v[210:211], v[14:15], v[206:207], v[210:211]
	v_pk_fma_f32 v[212:213], v[16:17], v[208:209], v[212:213]
	v_cvt_pk_bf16_f32 v72, v210, v211
	v_cvt_pk_bf16_f32 v73, v212, v213
	v_lshlrev_b32_e32 v206, 16, v106
	v_and_b32_e32 v207, 0xffff0000, v106
	v_lshlrev_b32_e32 v208, 16, v107
	v_and_b32_e32 v209, 0xffff0000, v107
	v_lshlrev_b32_e32 v210, 16, v74
	v_and_b32_e32 v211, 0xffff0000, v74
	v_lshlrev_b32_e32 v212, 16, v75
	v_and_b32_e32 v213, 0xffff0000, v75
	v_pk_fma_f32 v[210:211], v[18:19], v[206:207], v[210:211]
	v_pk_fma_f32 v[212:213], v[20:21], v[208:209], v[212:213]
	v_cvt_pk_bf16_f32 v74, v210, v211
	v_cvt_pk_bf16_f32 v75, v212, v213
	v_lshlrev_b32_e32 v206, 16, v108
	v_and_b32_e32 v207, 0xffff0000, v108
	v_lshlrev_b32_e32 v208, 16, v109
	v_and_b32_e32 v209, 0xffff0000, v109
	v_lshlrev_b32_e32 v210, 16, v76
	v_and_b32_e32 v211, 0xffff0000, v76
	v_lshlrev_b32_e32 v212, 16, v77
	v_and_b32_e32 v213, 0xffff0000, v77
	v_pk_fma_f32 v[210:211], v[22:23], v[206:207], v[210:211]
	v_pk_fma_f32 v[212:213], v[24:25], v[208:209], v[212:213]
	v_cvt_pk_bf16_f32 v76, v210, v211
	v_cvt_pk_bf16_f32 v77, v212, v213
	v_lshlrev_b32_e32 v206, 16, v110
	v_and_b32_e32 v207, 0xffff0000, v110
	v_lshlrev_b32_e32 v208, 16, v111
	v_and_b32_e32 v209, 0xffff0000, v111
	v_lshlrev_b32_e32 v210, 16, v78
	v_and_b32_e32 v211, 0xffff0000, v78
	v_lshlrev_b32_e32 v212, 16, v79
	v_and_b32_e32 v213, 0xffff0000, v79
	v_pk_fma_f32 v[210:211], v[26:27], v[206:207], v[210:211]
	v_pk_fma_f32 v[212:213], v[28:29], v[208:209], v[212:213]
	v_cvt_pk_bf16_f32 v78, v210, v211
	v_cvt_pk_bf16_f32 v79, v212, v213
	v_lshlrev_b32_e32 v206, 16, v112
	v_and_b32_e32 v207, 0xffff0000, v112
	v_lshlrev_b32_e32 v208, 16, v113
	v_and_b32_e32 v209, 0xffff0000, v113
	v_lshlrev_b32_e32 v210, 16, v80
	v_and_b32_e32 v211, 0xffff0000, v80
	v_lshlrev_b32_e32 v212, 16, v81
	v_and_b32_e32 v213, 0xffff0000, v81
	v_pk_fma_f32 v[210:211], v[30:31], v[206:207], v[210:211]
	v_pk_fma_f32 v[212:213], v[32:33], v[208:209], v[212:213]
	v_cvt_pk_bf16_f32 v80, v210, v211
	v_cvt_pk_bf16_f32 v81, v212, v213
	v_lshlrev_b32_e32 v206, 16, v114
	v_and_b32_e32 v207, 0xffff0000, v114
	v_lshlrev_b32_e32 v208, 16, v115
; __device__ __forceinline__ unsigned cvtpk(float lo, float hi) { f32x2 v = {lo, hi}; bf16x2_t b = __builtin_convertvector(v, bf16x2_t); return __builtin_bit_cast(unsigned, b); }
; __device__ __forceinline__ void branch_phase(LAS unsigned char* lds, const bf16_t* __restrict__ O, const bf16_t* __restrict__ Wb, const bf16_t* __restrict__ Gt, bf16_t* __restrict__ MG, int tg, int wv) {
;     ...
; #pragma unroll
;             for (int m = 0; m < 4; ++m)
; #pragma unroll
;                 for (int n = 0; n < 4; ++n) { const u32x2 g = gv[m][n], sp = sum[m][n];
;                     const float s0_ = __builtin_bit_cast(float, sp.x << 16) + acc[m][n][0] * __builtin_bit_cast(float, g.x << 16), s1_ = __builtin_bit_cast(float, sp.x & 0xffff0000u) + acc[m][n][1] * __builtin_bit_cast(float, g.x & 0xffff0000u);
;                     const float s2_ = __builtin_bit_cast(float, sp.y << 16) + acc[m][n][2] * __builtin_bit_cast(float, g.y << 16), s3_ = __builtin_bit_cast(float, sp.y & 0xffff0000u) + acc[m][n][3] * __builtin_bit_cast(float, g.y & 0xffff0000u);
;                     sum[m][n] = (u32x2){cvtpk(s0_, s1_), cvtpk(s2_, s3_)}; }
;         }
;     ...
; #pragma unroll
;         for (int m = 0; m < 4; ++m)
; #pragma unroll
;             for (int np = 0; np < 2; ++np) { u32x2 a = sum[m][2 * np], b = sum[m][2 * np + 1];
;                 asm volatile("s_nop 1\n\tv_permlane16_swap_b32 %0, %1\n\ts_nop 1" : "+v"(a.x), "+v"(b.x));
;                 asm volatile("s_nop 1\n\tv_permlane16_swap_b32 %0, %1\n\ts_nop 1" : "+v"(a.y), "+v"(b.y));
;                 *(u32x4*)(MG + (size_t)(rt * 128 + wm * 64 + m * 16 + fr) * 1024 + ct * 256 + wn * 64 + np * 32 + (fq & 1) * 16 + (fq >> 1) * 8) = (u32x4){a.x, a.y, b.x, b.y}; }
;     }
	v_and_b32_e32 v209, 0xffff0000, v115
	v_lshlrev_b32_e32 v210, 16, v82
	v_and_b32_e32 v211, 0xffff0000, v82
	v_lshlrev_b32_e32 v212, 16, v83
	v_and_b32_e32 v213, 0xffff0000, v83
	v_pk_fma_f32 v[210:211], v[34:35], v[206:207], v[210:211]
	v_pk_fma_f32 v[212:213], v[36:37], v[208:209], v[212:213]
	v_cvt_pk_bf16_f32 v82, v210, v211
	v_cvt_pk_bf16_f32 v83, v212, v213
	v_lshlrev_b32_e32 v206, 16, v116
	v_and_b32_e32 v207, 0xffff0000, v116
	v_lshlrev_b32_e32 v208, 16, v117
	v_and_b32_e32 v209, 0xffff0000, v117
	v_lshlrev_b32_e32 v210, 16, v84
	v_and_b32_e32 v211, 0xffff0000, v84
	v_lshlrev_b32_e32 v212, 16, v85
	v_and_b32_e32 v213, 0xffff0000, v85
	v_pk_fma_f32 v[210:211], v[38:39], v[206:207], v[210:211]
	v_pk_fma_f32 v[212:213], v[40:41], v[208:209], v[212:213]
	v_cvt_pk_bf16_f32 v84, v210, v211
	v_cvt_pk_bf16_f32 v85, v212, v213
	v_lshlrev_b32_e32 v206, 16, v118
	v_and_b32_e32 v207, 0xffff0000, v118
	v_lshlrev_b32_e32 v208, 16, v119
	v_and_b32_e32 v209, 0xffff0000, v119
	v_lshlrev_b32_e32 v210, 16, v86
	v_and_b32_e32 v211, 0xffff0000, v86
	v_lshlrev_b32_e32 v212, 16, v87
	v_and_b32_e32 v213, 0xffff0000, v87
	v_pk_fma_f32 v[210:211], v[42:43], v[206:207], v[210:211]
	v_pk_fma_f32 v[212:213], v[44:45], v[208:209], v[212:213]
	v_cvt_pk_bf16_f32 v86, v210, v211
	v_cvt_pk_bf16_f32 v87, v212, v213
	v_lshlrev_b32_e32 v206, 16, v120
	v_and_b32_e32 v207, 0xffff0000, v120
	v_lshlrev_b32_e32 v208, 16, v121
	v_and_b32_e32 v209, 0xffff0000, v121
	v_lshlrev_b32_e32 v210, 16, v88
	v_and_b32_e32 v211, 0xffff0000, v88
	v_lshlrev_b32_e32 v212, 16, v89
	v_and_b32_e32 v213, 0xffff0000, v89
	v_pk_fma_f32 v[210:211], v[46:47], v[206:207], v[210:211]
	v_pk_fma_f32 v[212:213], v[48:49], v[208:209], v[212:213]
	v_cvt_pk_bf16_f32 v88, v210, v211
	v_cvt_pk_bf16_f32 v89, v212, v213
	v_lshlrev_b32_e32 v206, 16, v122
	v_and_b32_e32 v207, 0xffff0000, v122
	v_lshlrev_b32_e32 v208, 16, v123
	v_and_b32_e32 v209, 0xffff0000, v123
	v_lshlrev_b32_e32 v210, 16, v90
	v_and_b32_e32 v211, 0xffff0000, v90
	v_lshlrev_b32_e32 v212, 16, v91
	v_and_b32_e32 v213, 0xffff0000, v91
	v_pk_fma_f32 v[210:211], v[50:51], v[206:207], v[210:211]
	v_pk_fma_f32 v[212:213], v[52:53], v[208:209], v[212:213]
	v_cvt_pk_bf16_f32 v90, v210, v211
	v_cvt_pk_bf16_f32 v91, v212, v213
	v_lshlrev_b32_e32 v206, 16, v124
	v_and_b32_e32 v207, 0xffff0000, v124
	v_lshlrev_b32_e32 v208, 16, v125
	v_and_b32_e32 v209, 0xffff0000, v125
	v_lshlrev_b32_e32 v210, 16, v92
	v_and_b32_e32 v211, 0xffff0000, v92
	v_lshlrev_b32_e32 v212, 16, v93
	v_and_b32_e32 v213, 0xffff0000, v93
	v_pk_fma_f32 v[210:211], v[54:55], v[206:207], v[210:211]
	v_pk_fma_f32 v[212:213], v[56:57], v[208:209], v[212:213]
	v_cvt_pk_bf16_f32 v92, v210, v211
	v_cvt_pk_bf16_f32 v93, v212, v213
	v_lshlrev_b32_e32 v206, 16, v126
	v_and_b32_e32 v207, 0xffff0000, v126
	v_lshlrev_b32_e32 v208, 16, v127
	v_and_b32_e32 v209, 0xffff0000, v127
	v_lshlrev_b32_e32 v210, 16, v94
	v_and_b32_e32 v211, 0xffff0000, v94
	v_lshlrev_b32_e32 v212, 16, v95
	v_and_b32_e32 v213, 0xffff0000, v95
	v_pk_fma_f32 v[210:211], v[58:59], v[206:207], v[210:211]
	v_pk_fma_f32 v[212:213], v[60:61], v[208:209], v[212:213]
	v_cvt_pk_bf16_f32 v94, v210, v211
	v_cvt_pk_bf16_f32 v95, v212, v213
	v_lshlrev_b32_e32 v206, 16, v128
	v_and_b32_e32 v207, 0xffff0000, v128
	v_lshlrev_b32_e32 v208, 16, v129
	v_and_b32_e32 v209, 0xffff0000, v129
	v_lshlrev_b32_e32 v210, 16, v96
	v_and_b32_e32 v211, 0xffff0000, v96
	v_lshlrev_b32_e32 v212, 16, v97
	v_and_b32_e32 v213, 0xffff0000, v97
	v_pk_fma_f32 v[210:211], v[62:63], v[206:207], v[210:211]
	v_pk_fma_f32 v[212:213], v[64:65], v[208:209], v[212:213]
	v_cvt_pk_bf16_f32 v96, v210, v211
	v_cvt_pk_bf16_f32 v97, v212, v213
	s_mov_b64 s[80:81], s[76:77]
	global_store_dwordx4 v205, v[66:69], s[80:81] offset:0
	s_nop 1
	global_store_dwordx4 v205, v[70:73], s[80:81] offset:64
	s_nop 1
	s_add_u32 s80, s80, 0x8000
	s_addc_u32 s81, s81, 0
	global_store_dwordx4 v205, v[74:77], s[80:81] offset:0
	s_nop 1
	global_store_dwordx4 v205, v[78:81], s[80:81] offset:64
	s_nop 1
	s_add_u32 s80, s80, 0x8000
	s_addc_u32 s81, s81, 0
	global_store_dwordx4 v205, v[82:85], s[80:81] offset:0
	s_nop 1
	global_store_dwordx4 v205, v[86:89], s[80:81] offset:64
	s_nop 1
	s_add_u32 s80, s80, 0x8000
	s_addc_u32 s81, s81, 0
	global_store_dwordx4 v205, v[90:93], s[80:81] offset:0
	s_nop 1
	global_store_dwordx4 v205, v[94:97], s[80:81] offset:64
	s_nop 1
	s_add_i32 s5, s5, s4
	s_cmp_lt_i32 s5, s6
	s_cbranch_scc0 .LBB0_283
	s_lshl_b32 s79, s62, 2
	s_add_u32 s74, s74, s79
	s_addc_u32 s75, s75, 0
	s_add_u32 s76, s76, s62
	s_addc_u32 s77, s77, 0
	s_mov_b32 s79, s82
	s_mov_b32 s82, s83
	s_mov_b32 s83, s84
	s_mov_b32 s84, s79
	s_mov_b32 s79, s85
	s_mov_b32 s85, s60
	s_mov_b32 s60, s61
	s_mov_b32 s61, s79
	v_mov_b32_e32 v206, v214
	v_mov_b32_e32 v214, v215
	v_mov_b32_e32 v215, v216
	v_mov_b32_e32 v216, v206
	v_mov_b32_e32 v206, v217
	v_mov_b32_e32 v217, v218
	v_mov_b32_e32 v218, v219
	v_mov_b32_e32 v219, v206
	s_branch .Lph6_tile
